# GEMM K-loop heads aligned to 64 bytes (s_nop fill), otherwise the final-norm version
# baseline (speedup 1.0000x reference)
.LBB0_372:
	s_ashr_i32 s21, s20, 31
	s_lshl_b64 s[22:23], s[20:21], 19
	s_add_u32 s22, s96, s22
	s_addc_u32 s23, s97, s23
	s_and_b64 s[24:25], s[4:5], exec
	s_cselect_b32 s21, s23, s29
	s_cselect_b32 s27, s22, s28
	s_ashr_i32 s13, s12, 31
	s_lshl_b64 s[24:25], s[12:13], 19
	s_add_u32 s24, s14, s24
	s_addc_u32 s25, s15, s25
	s_and_b64 s[36:37], s[4:5], exec
	s_cselect_b32 s13, s25, s31
	s_cselect_b32 s48, s24, s30
	s_add_u32 s49, s30, 0x100
	s_addc_u32 s50, s31, 0
	s_mov_b32 s51, -2
	ds_read_b128 v[150:153], v180
	ds_read_b128 v[154:157], v180 offset:1024
	ds_read_b128 v[158:161], v180 offset:2048
	ds_read_b128 v[162:165], v180 offset:3072
	ds_read_b128 v[184:187], v181
	ds_read_b128 v[188:191], v181 offset:1024
	ds_read_b128 v[192:195], v181 offset:2048
	ds_read_b128 v[196:199], v181 offset:3072
	s_add_u32 s30, s28, 0x100
	s_addc_u32 s31, s29, 0
	s_cmp_eq_u32 s51, 12
	s_cselect_b32 s39, s21, s31
	s_cselect_b32 s38, s27, s30
	s_cselect_b32 s37, s13, s50
	s_cselect_b32 s36, s48, s49
	v_lshl_add_u64 v[166:167], s[28:29], 0, v[142:143]
	s_add_i32 m0, s17, 0xc000
	ds_read_b128 v[200:203], v182
	ds_read_b128 v[204:207], v182 offset:1024
	ds_read_b128 v[208:211], v182 offset:2048
	ds_read_b128 v[212:215], v182 offset:3072
	ds_read_b128 v[216:219], v182 offset:4096
	ds_read_b128 v[220:223], v182 offset:5120
	ds_read_b128 v[224:227], v182 offset:6144
	ds_read_b128 v[228:231], v182 offset:7168
	global_load_lds_dwordx4 v[166:167], off
	v_lshl_add_u64 v[166:167], s[28:29], 0, v[144:145]
	s_add_i32 m0, s17, 0xe000
	s_nop 0
	global_load_lds_dwordx4 v[166:167], off
	s_waitcnt vmcnt(8)
	s_waitcnt lgkmcnt(0)
	s_barrier
	s_setprio 1
	s_waitcnt lgkmcnt(0)
	v_mfma_f32_16x16x32_bf16 v[82:85], v[150:153], v[200:203], 0
	v_mfma_f32_16x16x32_bf16 v[78:81], v[158:161], v[200:203], 0
	v_mfma_f32_16x16x32_bf16 v[70:73], v[150:153], v[208:211], 0
	v_mfma_f32_16x16x32_bf16 v[66:69], v[158:161], v[208:211], 0
	v_mfma_f32_16x16x32_bf16 v[62:65], v[150:153], v[216:219], 0
	v_mfma_f32_16x16x32_bf16 v[58:61], v[158:161], v[216:219], 0
	v_mfma_f32_16x16x32_bf16 v[54:57], v[150:153], v[224:227], 0
	v_mfma_f32_16x16x32_bf16 v[50:53], v[158:161], v[224:227], 0
	v_mfma_f32_16x16x32_bf16 v[82:85], v[154:157], v[204:207], v[82:85]
	v_mfma_f32_16x16x32_bf16 v[78:81], v[162:165], v[204:207], v[78:81]
	v_mfma_f32_16x16x32_bf16 v[70:73], v[154:157], v[212:215], v[70:73]
	v_mfma_f32_16x16x32_bf16 v[66:69], v[162:165], v[212:215], v[66:69]
	v_mfma_f32_16x16x32_bf16 v[62:65], v[154:157], v[220:223], v[62:65]
	v_mfma_f32_16x16x32_bf16 v[58:61], v[162:165], v[220:223], v[58:61]
	v_mfma_f32_16x16x32_bf16 v[54:57], v[154:157], v[228:231], v[54:57]
	v_mfma_f32_16x16x32_bf16 v[50:53], v[162:165], v[228:231], v[50:53]
	s_setprio 0
	s_setprio 1
	v_mfma_f32_16x16x32_bf16 v[126:129], v[184:187], v[200:203], 0
	v_mfma_f32_16x16x32_bf16 v[122:125], v[192:195], v[200:203], 0
	v_mfma_f32_16x16x32_bf16 v[118:121], v[184:187], v[208:211], 0
	v_mfma_f32_16x16x32_bf16 v[114:117], v[192:195], v[208:211], 0
	v_mfma_f32_16x16x32_bf16 v[110:113], v[184:187], v[216:219], 0
	v_mfma_f32_16x16x32_bf16 v[106:109], v[192:195], v[216:219], 0
	v_mfma_f32_16x16x32_bf16 v[102:105], v[184:187], v[224:227], 0
	v_mfma_f32_16x16x32_bf16 v[98:101], v[192:195], v[224:227], 0
	v_mfma_f32_16x16x32_bf16 v[126:129], v[188:191], v[204:207], v[126:129]
	v_mfma_f32_16x16x32_bf16 v[122:125], v[196:199], v[204:207], v[122:125]
	v_mfma_f32_16x16x32_bf16 v[118:121], v[188:191], v[212:215], v[118:121]
	v_mfma_f32_16x16x32_bf16 v[114:117], v[196:199], v[212:215], v[114:117]
	v_mfma_f32_16x16x32_bf16 v[110:113], v[188:191], v[220:223], v[110:113]
	v_mfma_f32_16x16x32_bf16 v[106:109], v[196:199], v[220:223], v[106:109]
	v_mfma_f32_16x16x32_bf16 v[102:105], v[188:191], v[228:231], v[102:105]
	v_mfma_f32_16x16x32_bf16 v[98:101], v[196:199], v[228:231], v[98:101]
	s_setprio 0
	s_barrier
	s_add_i32 s28, s45, s16
	v_lshl_add_u64 v[166:167], s[36:37], 0, v[134:135]
	s_mov_b32 m0, s28
	ds_read_b128 v[200:203], v182 offset:16384
	ds_read_b128 v[204:207], v182 offset:17408
	ds_read_b128 v[208:211], v182 offset:18432
	ds_read_b128 v[212:215], v182 offset:19456
	ds_read_b128 v[216:219], v182 offset:20480
	ds_read_b128 v[220:223], v182 offset:21504
	ds_read_b128 v[224:227], v182 offset:22528
	ds_read_b128 v[228:231], v182 offset:23552
	global_load_lds_dwordx4 v[166:167], off
	s_add_i32 m0, s28, 0x2000
	s_add_u32 s28, s36, 0x40000
	v_lshl_add_u64 v[232:233], s[36:37], 0, v[136:137]
	s_addc_u32 s29, s37, 0
	s_add_i32 s52, s46, s16
	global_load_lds_dwordx4 v[232:233], off
	v_lshl_add_u64 v[234:235], s[28:29], 0, v[134:135]
	s_mov_b32 m0, s52
	v_lshl_add_u64 v[236:237], s[38:39], 0, v[130:131]
	global_load_lds_dwordx4 v[234:235], off
	v_lshl_add_u64 v[234:235], s[28:29], 0, v[136:137]
	s_add_i32 m0, s52, 0x2000
	s_nop 0
	global_load_lds_dwordx4 v[234:235], off
	v_lshl_add_u64 v[234:235], s[38:39], 0, v[132:133]
	s_mov_b32 m0, s17
	s_nop 0
	global_load_lds_dwordx4 v[234:235], off
	s_mov_b32 m0, s34
	s_nop 0
	global_load_lds_dwordx4 v[236:237], off
	s_waitcnt vmcnt(8)
	s_waitcnt lgkmcnt(0)
	s_barrier
	s_setprio 1
	s_waitcnt lgkmcnt(0)
	v_mfma_f32_16x16x32_bf16 v[38:41], v[150:153], v[200:203], 0
	v_mfma_f32_16x16x32_bf16 v[34:37], v[158:161], v[200:203], 0
	v_mfma_f32_16x16x32_bf16 v[26:29], v[150:153], v[208:211], 0
	v_mfma_f32_16x16x32_bf16 v[22:25], v[158:161], v[208:211], 0
	v_mfma_f32_16x16x32_bf16 v[14:17], v[150:153], v[216:219], 0
	v_mfma_f32_16x16x32_bf16 v[10:13], v[158:161], v[216:219], 0
	v_mfma_f32_16x16x32_bf16 v[6:9], v[150:153], v[224:227], 0
	v_mfma_f32_16x16x32_bf16 v[2:5], v[158:161], v[224:227], 0
	v_mfma_f32_16x16x32_bf16 v[38:41], v[154:157], v[204:207], v[38:41]
	v_mfma_f32_16x16x32_bf16 v[34:37], v[162:165], v[204:207], v[34:37]
	v_mfma_f32_16x16x32_bf16 v[26:29], v[154:157], v[212:215], v[26:29]
	v_mfma_f32_16x16x32_bf16 v[22:25], v[162:165], v[212:215], v[22:25]
	v_mfma_f32_16x16x32_bf16 v[14:17], v[154:157], v[220:223], v[14:17]
	v_mfma_f32_16x16x32_bf16 v[10:13], v[162:165], v[220:223], v[10:13]
	v_mfma_f32_16x16x32_bf16 v[6:9], v[154:157], v[228:231], v[6:9]
	v_mfma_f32_16x16x32_bf16 v[2:5], v[162:165], v[228:231], v[2:5]
	s_setprio 0
	s_setprio 1
	v_mfma_f32_16x16x32_bf16 v[94:97], v[184:187], v[200:203], 0
	v_mfma_f32_16x16x32_bf16 v[90:93], v[192:195], v[200:203], 0
	v_mfma_f32_16x16x32_bf16 v[86:89], v[184:187], v[208:211], 0
	v_mfma_f32_16x16x32_bf16 v[74:77], v[192:195], v[208:211], 0
	v_mfma_f32_16x16x32_bf16 v[46:49], v[184:187], v[216:219], 0
	v_mfma_f32_16x16x32_bf16 v[42:45], v[192:195], v[216:219], 0
	v_mfma_f32_16x16x32_bf16 v[30:33], v[184:187], v[224:227], 0
	v_mfma_f32_16x16x32_bf16 v[18:21], v[192:195], v[224:227], 0
	v_mfma_f32_16x16x32_bf16 v[94:97], v[188:191], v[204:207], v[94:97]
	v_mfma_f32_16x16x32_bf16 v[90:93], v[196:199], v[204:207], v[90:93]
	v_mfma_f32_16x16x32_bf16 v[86:89], v[188:191], v[212:215], v[86:89]
	v_mfma_f32_16x16x32_bf16 v[74:77], v[196:199], v[212:215], v[74:77]
	v_mfma_f32_16x16x32_bf16 v[46:49], v[188:191], v[220:223], v[46:49]
	v_mfma_f32_16x16x32_bf16 v[42:45], v[196:199], v[220:223], v[42:45]
	v_mfma_f32_16x16x32_bf16 v[30:33], v[188:191], v[228:231], v[30:33]
	v_mfma_f32_16x16x32_bf16 v[18:21], v[196:199], v[228:231], v[18:21]
	s_setprio 0
	s_barrier
	s_add_i32 s52, 0, 0x18000
	v_add_u32_e32 v138, s52, v178
	s_add_i32 s53, 0, 0x1c000
	ds_read_b128 v[150:153], v138
	ds_read_b128 v[154:157], v138 offset:1024
	ds_read_b128 v[158:161], v138 offset:2048
	ds_read_b128 v[162:165], v138 offset:3072
	v_add_u32_e32 v138, s53, v178
	ds_read_b128 v[184:187], v138
	ds_read_b128 v[188:191], v138 offset:1024
	ds_read_b128 v[192:195], v138 offset:2048
	ds_read_b128 v[196:199], v138 offset:3072
	s_add_u32 s28, s38, 0x40000
	s_addc_u32 s29, s39, 0
	s_mov_b32 m0, s35
	v_lshl_add_u64 v[238:239], s[28:29], 0, v[132:133]
	ds_read_b128 v[200:203], v182 offset:32768
	ds_read_b128 v[204:207], v182 offset:33792
	ds_read_b128 v[208:211], v182 offset:34816
	ds_read_b128 v[212:215], v182 offset:35840
	ds_read_b128 v[216:219], v182 offset:36864
	ds_read_b128 v[220:223], v182 offset:37888
	ds_read_b128 v[224:227], v182 offset:38912
	ds_read_b128 v[228:231], v182 offset:39936
	global_load_lds_dwordx4 v[238:239], off
	v_lshl_add_u64 v[238:239], s[28:29], 0, v[130:131]
	s_mov_b32 m0, s40
	s_nop 0
	global_load_lds_dwordx4 v[238:239], off
	s_waitcnt vmcnt(8)
	s_waitcnt lgkmcnt(0)
	s_barrier
	s_setprio 1
	s_waitcnt lgkmcnt(0)
	v_mfma_f32_16x16x32_bf16 v[82:85], v[150:153], v[200:203], v[82:85]
	v_mfma_f32_16x16x32_bf16 v[78:81], v[158:161], v[200:203], v[78:81]
	v_mfma_f32_16x16x32_bf16 v[70:73], v[150:153], v[208:211], v[70:73]
	v_mfma_f32_16x16x32_bf16 v[66:69], v[158:161], v[208:211], v[66:69]
	v_mfma_f32_16x16x32_bf16 v[62:65], v[150:153], v[216:219], v[62:65]
	v_mfma_f32_16x16x32_bf16 v[58:61], v[158:161], v[216:219], v[58:61]
	v_mfma_f32_16x16x32_bf16 v[54:57], v[150:153], v[224:227], v[54:57]
	v_mfma_f32_16x16x32_bf16 v[50:53], v[158:161], v[224:227], v[50:53]
	v_mfma_f32_16x16x32_bf16 v[82:85], v[154:157], v[204:207], v[82:85]
	v_mfma_f32_16x16x32_bf16 v[78:81], v[162:165], v[204:207], v[78:81]
	v_mfma_f32_16x16x32_bf16 v[70:73], v[154:157], v[212:215], v[70:73]
	v_mfma_f32_16x16x32_bf16 v[66:69], v[162:165], v[212:215], v[66:69]
	v_mfma_f32_16x16x32_bf16 v[62:65], v[154:157], v[220:223], v[62:65]
	v_mfma_f32_16x16x32_bf16 v[58:61], v[162:165], v[220:223], v[58:61]
	v_mfma_f32_16x16x32_bf16 v[54:57], v[154:157], v[228:231], v[54:57]
	v_mfma_f32_16x16x32_bf16 v[50:53], v[162:165], v[228:231], v[50:53]
	s_setprio 0
	s_setprio 1
	v_mfma_f32_16x16x32_bf16 v[126:129], v[184:187], v[200:203], v[126:129]
	v_mfma_f32_16x16x32_bf16 v[122:125], v[192:195], v[200:203], v[122:125]
	v_mfma_f32_16x16x32_bf16 v[118:121], v[184:187], v[208:211], v[118:121]
	v_mfma_f32_16x16x32_bf16 v[114:117], v[192:195], v[208:211], v[114:117]
	v_mfma_f32_16x16x32_bf16 v[110:113], v[184:187], v[216:219], v[110:113]
	v_mfma_f32_16x16x32_bf16 v[106:109], v[192:195], v[216:219], v[106:109]
	v_mfma_f32_16x16x32_bf16 v[102:105], v[184:187], v[224:227], v[102:105]
	v_mfma_f32_16x16x32_bf16 v[98:101], v[192:195], v[224:227], v[98:101]
	v_mfma_f32_16x16x32_bf16 v[126:129], v[188:191], v[204:207], v[126:129]
	v_mfma_f32_16x16x32_bf16 v[122:125], v[196:199], v[204:207], v[122:125]
	v_mfma_f32_16x16x32_bf16 v[118:121], v[188:191], v[212:215], v[118:121]
	v_mfma_f32_16x16x32_bf16 v[114:117], v[196:199], v[212:215], v[114:117]
	v_mfma_f32_16x16x32_bf16 v[110:113], v[188:191], v[220:223], v[110:113]
	v_mfma_f32_16x16x32_bf16 v[106:109], v[196:199], v[220:223], v[106:109]
	v_mfma_f32_16x16x32_bf16 v[102:105], v[188:191], v[228:231], v[102:105]
	v_mfma_f32_16x16x32_bf16 v[98:101], v[196:199], v[228:231], v[98:101]
	s_setprio 0
	s_barrier
	s_add_i32 s28, s52, s16
	v_lshl_add_u64 v[166:167], v[166:167], 0, s[6:7]
	s_mov_b32 m0, s28
	ds_read_b128 v[200:203], v182 offset:49152
	ds_read_b128 v[204:207], v182 offset:50176
	ds_read_b128 v[208:211], v182 offset:51200
	ds_read_b128 v[212:215], v182 offset:52224
	ds_read_b128 v[216:219], v182 offset:53248
	ds_read_b128 v[220:223], v182 offset:54272
	ds_read_b128 v[224:227], v182 offset:55296
	ds_read_b128 v[228:231], v182 offset:56320
	global_load_lds_dwordx4 v[166:167], off
	s_add_i32 m0, s28, 0x2000
	s_add_u32 s28, s36, 0x40080
	v_lshl_add_u64 v[166:167], v[232:233], 0, s[6:7]
	s_addc_u32 s29, s37, 0
	s_add_i32 s36, s53, s16
	global_load_lds_dwordx4 v[166:167], off
	v_lshl_add_u64 v[166:167], s[28:29], 0, v[134:135]
	s_mov_b32 m0, s36
	s_nop 0
	global_load_lds_dwordx4 v[166:167], off
	v_lshl_add_u64 v[166:167], s[28:29], 0, v[136:137]
	s_add_i32 m0, s36, 0x2000
	s_nop 0
	global_load_lds_dwordx4 v[166:167], off
	v_lshl_add_u64 v[166:167], v[234:235], 0, s[6:7]
	s_mov_b32 m0, s42
	s_nop 0
	global_load_lds_dwordx4 v[166:167], off
	v_lshl_add_u64 v[166:167], v[236:237], 0, s[6:7]
	s_mov_b32 m0, s43
	s_nop 0
	global_load_lds_dwordx4 v[166:167], off
	s_waitcnt vmcnt(8)
	s_waitcnt lgkmcnt(0)
	s_barrier
	s_setprio 1
	s_waitcnt lgkmcnt(0)
	v_mfma_f32_16x16x32_bf16 v[38:41], v[150:153], v[200:203], v[38:41]
	v_mfma_f32_16x16x32_bf16 v[34:37], v[158:161], v[200:203], v[34:37]
	v_mfma_f32_16x16x32_bf16 v[26:29], v[150:153], v[208:211], v[26:29]
	v_mfma_f32_16x16x32_bf16 v[22:25], v[158:161], v[208:211], v[22:25]
	v_mfma_f32_16x16x32_bf16 v[14:17], v[150:153], v[216:219], v[14:17]
	v_mfma_f32_16x16x32_bf16 v[10:13], v[158:161], v[216:219], v[10:13]
	v_mfma_f32_16x16x32_bf16 v[6:9], v[150:153], v[224:227], v[6:9]
	v_mfma_f32_16x16x32_bf16 v[2:5], v[158:161], v[224:227], v[2:5]
	v_mfma_f32_16x16x32_bf16 v[38:41], v[154:157], v[204:207], v[38:41]
	v_mfma_f32_16x16x32_bf16 v[34:37], v[162:165], v[204:207], v[34:37]
	v_mfma_f32_16x16x32_bf16 v[26:29], v[154:157], v[212:215], v[26:29]
	v_mfma_f32_16x16x32_bf16 v[22:25], v[162:165], v[212:215], v[22:25]
	v_mfma_f32_16x16x32_bf16 v[14:17], v[154:157], v[220:223], v[14:17]
	v_mfma_f32_16x16x32_bf16 v[10:13], v[162:165], v[220:223], v[10:13]
	v_mfma_f32_16x16x32_bf16 v[6:9], v[154:157], v[228:231], v[6:9]
	v_mfma_f32_16x16x32_bf16 v[2:5], v[162:165], v[228:231], v[2:5]
	s_setprio 0
	s_setprio 1
	v_mfma_f32_16x16x32_bf16 v[94:97], v[184:187], v[200:203], v[94:97]
	v_mfma_f32_16x16x32_bf16 v[90:93], v[192:195], v[200:203], v[90:93]
	v_mfma_f32_16x16x32_bf16 v[86:89], v[184:187], v[208:211], v[86:89]
	v_mfma_f32_16x16x32_bf16 v[74:77], v[192:195], v[208:211], v[74:77]
	v_mfma_f32_16x16x32_bf16 v[46:49], v[184:187], v[216:219], v[46:49]
	v_mfma_f32_16x16x32_bf16 v[42:45], v[192:195], v[216:219], v[42:45]
	v_mfma_f32_16x16x32_bf16 v[30:33], v[184:187], v[224:227], v[30:33]
	v_mfma_f32_16x16x32_bf16 v[18:21], v[192:195], v[224:227], v[18:21]
	v_mfma_f32_16x16x32_bf16 v[94:97], v[188:191], v[204:207], v[94:97]
	v_mfma_f32_16x16x32_bf16 v[90:93], v[196:199], v[204:207], v[90:93]
	v_mfma_f32_16x16x32_bf16 v[86:89], v[188:191], v[212:215], v[86:89]
	v_mfma_f32_16x16x32_bf16 v[74:77], v[196:199], v[212:215], v[74:77]
	v_mfma_f32_16x16x32_bf16 v[46:49], v[188:191], v[220:223], v[46:49]
	v_mfma_f32_16x16x32_bf16 v[42:45], v[196:199], v[220:223], v[42:45]
	v_mfma_f32_16x16x32_bf16 v[30:33], v[188:191], v[228:231], v[30:33]
	v_mfma_f32_16x16x32_bf16 v[18:21], v[196:199], v[228:231], v[18:21]
	s_setprio 0
	s_barrier
	s_add_i32 s51, s51, 2
	s_add_u32 s49, s49, 0x100
	s_addc_u32 s50, s50, 0
	s_cmp_gt_u32 s51, 13
	s_mov_b64 s[28:29], s[30:31]
	s_cbranch_scc0 .LBB0_373
	s_branch .Lpeel_exit_373
	.p2alignl 6, 3212836864

.LBB0_404:
	s_ashr_i32 s29, s28, 31
	s_lshl_b64 s[30:31], s[28:29], 19
	s_add_u32 s30, s14, s30
	s_addc_u32 s31, s15, s31
	s_and_b64 s[34:35], s[24:25], exec
	s_cselect_b32 s5, s31, s41
	s_cselect_b32 s29, s30, s40
	s_ashr_i32 s27, s26, 31
	s_lshl_b64 s[34:35], s[26:27], 19
	s_add_u32 s36, s16, s34
	s_addc_u32 s37, s17, s35
	s_and_b64 s[34:35], s[24:25], exec
	s_cselect_b32 s27, s37, s43
	s_cselect_b32 s34, s36, s42
	s_add_u32 s35, s42, 0x100
	s_addc_u32 s39, s43, 0
	s_mov_b32 s61, -2
	ds_read_b128 v[140:143], v156
	ds_read_b128 v[144:147], v156 offset:1024
	ds_read_b128 v[148:151], v156 offset:2048
	ds_read_b128 v[164:167], v156 offset:3072
	ds_read_b128 v[168:171], v157
	ds_read_b128 v[178:181], v157 offset:1024
	ds_read_b128 v[182:185], v157 offset:2048
	ds_read_b128 v[186:189], v157 offset:3072
	s_add_u32 s42, s40, 0x100
	s_addc_u32 s43, s41, 0
	s_cmp_eq_u32 s61, 12
	s_cselect_b32 s47, s5, s43
	s_cselect_b32 s46, s29, s42
	s_cselect_b32 s45, s27, s39
	s_cselect_b32 s44, s34, s35
	v_lshl_add_u64 v[152:153], s[40:41], 0, v[136:137]
	s_add_i32 m0, s49, 0xc000
	ds_read_b128 v[190:193], v158
	ds_read_b128 v[194:197], v158 offset:1024
	ds_read_b128 v[198:201], v158 offset:2048
	ds_read_b128 v[202:205], v158 offset:3072
	ds_read_b128 v[206:209], v158 offset:4096
	ds_read_b128 v[210:213], v158 offset:5120
	ds_read_b128 v[214:217], v158 offset:6144
	ds_read_b128 v[218:221], v158 offset:7168
	global_load_lds_dwordx4 v[152:153], off
	v_lshl_add_u64 v[152:153], s[40:41], 0, v[138:139]
	s_add_i32 m0, s49, 0xe000
	s_nop 0
	global_load_lds_dwordx4 v[152:153], off
	s_waitcnt vmcnt(8)
	s_waitcnt lgkmcnt(0)
	s_barrier
	s_setprio 1
	s_waitcnt lgkmcnt(0)
	v_mfma_f32_16x16x32_bf16 v[126:129], v[140:143], v[190:193], 0
	v_mfma_f32_16x16x32_bf16 v[122:125], v[148:151], v[190:193], 0
	v_mfma_f32_16x16x32_bf16 v[110:113], v[140:143], v[198:201], 0
	v_mfma_f32_16x16x32_bf16 v[106:109], v[148:151], v[198:201], 0
	v_mfma_f32_16x16x32_bf16 v[94:97], v[140:143], v[206:209], 0
	v_mfma_f32_16x16x32_bf16 v[90:93], v[148:151], v[206:209], 0
	v_mfma_f32_16x16x32_bf16 v[78:81], v[140:143], v[214:217], 0
	v_mfma_f32_16x16x32_bf16 v[74:77], v[148:151], v[214:217], 0
	v_mfma_f32_16x16x32_bf16 v[126:129], v[144:147], v[194:197], v[126:129]
	v_mfma_f32_16x16x32_bf16 v[122:125], v[164:167], v[194:197], v[122:125]
	v_mfma_f32_16x16x32_bf16 v[110:113], v[144:147], v[202:205], v[110:113]
	v_mfma_f32_16x16x32_bf16 v[106:109], v[164:167], v[202:205], v[106:109]
	v_mfma_f32_16x16x32_bf16 v[94:97], v[144:147], v[210:213], v[94:97]
	v_mfma_f32_16x16x32_bf16 v[90:93], v[164:167], v[210:213], v[90:93]
	v_mfma_f32_16x16x32_bf16 v[78:81], v[144:147], v[218:221], v[78:81]
	v_mfma_f32_16x16x32_bf16 v[74:77], v[164:167], v[218:221], v[74:77]
	s_setprio 0
	s_setprio 1
	v_mfma_f32_16x16x32_bf16 v[118:121], v[168:171], v[190:193], 0
	v_mfma_f32_16x16x32_bf16 v[114:117], v[182:185], v[190:193], 0
	v_mfma_f32_16x16x32_bf16 v[102:105], v[168:171], v[198:201], 0
	v_mfma_f32_16x16x32_bf16 v[98:101], v[182:185], v[198:201], 0
	v_mfma_f32_16x16x32_bf16 v[86:89], v[168:171], v[206:209], 0
	v_mfma_f32_16x16x32_bf16 v[82:85], v[182:185], v[206:209], 0
	v_mfma_f32_16x16x32_bf16 v[70:73], v[168:171], v[214:217], 0
	v_mfma_f32_16x16x32_bf16 v[66:69], v[182:185], v[214:217], 0
	v_mfma_f32_16x16x32_bf16 v[118:121], v[178:181], v[194:197], v[118:121]
	v_mfma_f32_16x16x32_bf16 v[114:117], v[186:189], v[194:197], v[114:117]
	v_mfma_f32_16x16x32_bf16 v[102:105], v[178:181], v[202:205], v[102:105]
	v_mfma_f32_16x16x32_bf16 v[98:101], v[186:189], v[202:205], v[98:101]
	v_mfma_f32_16x16x32_bf16 v[86:89], v[178:181], v[210:213], v[86:89]
	v_mfma_f32_16x16x32_bf16 v[82:85], v[186:189], v[210:213], v[82:85]
	v_mfma_f32_16x16x32_bf16 v[70:73], v[178:181], v[218:221], v[70:73]
	v_mfma_f32_16x16x32_bf16 v[66:69], v[186:189], v[218:221], v[66:69]
	s_setprio 0
	s_barrier
	s_add_i32 s40, s59, s48
	v_lshl_add_u64 v[152:153], s[44:45], 0, v[132:133]
	s_mov_b32 m0, s40
	ds_read_b128 v[190:193], v158 offset:16384
	ds_read_b128 v[194:197], v158 offset:17408
	ds_read_b128 v[198:201], v158 offset:18432
	ds_read_b128 v[202:205], v158 offset:19456
	ds_read_b128 v[206:209], v158 offset:20480
	ds_read_b128 v[210:213], v158 offset:21504
	ds_read_b128 v[214:217], v158 offset:22528
	ds_read_b128 v[218:221], v158 offset:23552
	global_load_lds_dwordx4 v[152:153], off
	s_add_i32 m0, s40, 0x2000
	s_add_u32 s40, s44, 0x40000
	v_lshl_add_u64 v[172:173], s[44:45], 0, v[130:131]
	s_addc_u32 s41, s45, 0
	s_add_i32 s62, s60, s48
	global_load_lds_dwordx4 v[172:173], off
	v_lshl_add_u64 v[222:223], s[40:41], 0, v[132:133]
	s_mov_b32 m0, s62
	v_lshl_add_u64 v[224:225], s[46:47], 0, v[130:131]
	global_load_lds_dwordx4 v[222:223], off
	v_lshl_add_u64 v[222:223], s[40:41], 0, v[130:131]
	s_add_i32 m0, s62, 0x2000
	s_nop 0
	global_load_lds_dwordx4 v[222:223], off
	v_lshl_add_u64 v[222:223], s[46:47], 0, v[132:133]
	s_mov_b32 m0, s49
	s_nop 0
	global_load_lds_dwordx4 v[222:223], off
	s_mov_b32 m0, s50
	s_nop 0
	global_load_lds_dwordx4 v[224:225], off
	s_waitcnt vmcnt(8)
	s_waitcnt lgkmcnt(0)
	s_barrier
	s_setprio 1
	s_waitcnt lgkmcnt(0)
	v_mfma_f32_16x16x32_bf16 v[62:65], v[140:143], v[190:193], 0
	v_mfma_f32_16x16x32_bf16 v[58:61], v[148:151], v[190:193], 0
	v_mfma_f32_16x16x32_bf16 v[46:49], v[140:143], v[198:201], 0
	v_mfma_f32_16x16x32_bf16 v[42:45], v[148:151], v[198:201], 0
	v_mfma_f32_16x16x32_bf16 v[30:33], v[140:143], v[206:209], 0
	v_mfma_f32_16x16x32_bf16 v[26:29], v[148:151], v[206:209], 0
	v_mfma_f32_16x16x32_bf16 v[14:17], v[140:143], v[214:217], 0
	v_mfma_f32_16x16x32_bf16 v[10:13], v[148:151], v[214:217], 0
	v_mfma_f32_16x16x32_bf16 v[62:65], v[144:147], v[194:197], v[62:65]
	v_mfma_f32_16x16x32_bf16 v[58:61], v[164:167], v[194:197], v[58:61]
	v_mfma_f32_16x16x32_bf16 v[46:49], v[144:147], v[202:205], v[46:49]
	v_mfma_f32_16x16x32_bf16 v[42:45], v[164:167], v[202:205], v[42:45]
	v_mfma_f32_16x16x32_bf16 v[30:33], v[144:147], v[210:213], v[30:33]
	v_mfma_f32_16x16x32_bf16 v[26:29], v[164:167], v[210:213], v[26:29]
	v_mfma_f32_16x16x32_bf16 v[14:17], v[144:147], v[218:221], v[14:17]
	v_mfma_f32_16x16x32_bf16 v[10:13], v[164:167], v[218:221], v[10:13]
	s_setprio 0
	s_setprio 1
	v_mfma_f32_16x16x32_bf16 v[54:57], v[168:171], v[190:193], 0
	v_mfma_f32_16x16x32_bf16 v[50:53], v[182:185], v[190:193], 0
	v_mfma_f32_16x16x32_bf16 v[38:41], v[168:171], v[198:201], 0
	v_mfma_f32_16x16x32_bf16 v[34:37], v[182:185], v[198:201], 0
	v_mfma_f32_16x16x32_bf16 v[22:25], v[168:171], v[206:209], 0
	v_mfma_f32_16x16x32_bf16 v[18:21], v[182:185], v[206:209], 0
	v_mfma_f32_16x16x32_bf16 v[6:9], v[168:171], v[214:217], 0
	v_mfma_f32_16x16x32_bf16 v[2:5], v[182:185], v[214:217], 0
	v_mfma_f32_16x16x32_bf16 v[54:57], v[178:181], v[194:197], v[54:57]
	v_mfma_f32_16x16x32_bf16 v[50:53], v[186:189], v[194:197], v[50:53]
	v_mfma_f32_16x16x32_bf16 v[38:41], v[178:181], v[202:205], v[38:41]
	v_mfma_f32_16x16x32_bf16 v[34:37], v[186:189], v[202:205], v[34:37]
	v_mfma_f32_16x16x32_bf16 v[22:25], v[178:181], v[210:213], v[22:25]
	v_mfma_f32_16x16x32_bf16 v[18:21], v[186:189], v[210:213], v[18:21]
	v_mfma_f32_16x16x32_bf16 v[6:9], v[178:181], v[218:221], v[6:9]
	v_mfma_f32_16x16x32_bf16 v[2:5], v[186:189], v[218:221], v[2:5]
	s_setprio 0
	s_barrier
	s_add_i32 s62, 0, 0x18000
	v_add_u32_e32 v134, s62, v154
	s_add_i32 s63, 0, 0x1c000
	ds_read_b128 v[140:143], v134
	ds_read_b128 v[144:147], v134 offset:1024
	ds_read_b128 v[148:151], v134 offset:2048
	ds_read_b128 v[164:167], v134 offset:3072
	v_add_u32_e32 v134, s63, v154
	ds_read_b128 v[168:171], v134
	ds_read_b128 v[178:181], v134 offset:1024
	ds_read_b128 v[182:185], v134 offset:2048
	ds_read_b128 v[186:189], v134 offset:3072
	s_add_u32 s40, s46, 0x40000
	s_addc_u32 s41, s47, 0
	s_mov_b32 m0, s51
	v_lshl_add_u64 v[226:227], s[40:41], 0, v[132:133]
	ds_read_b128 v[190:193], v158 offset:32768
	ds_read_b128 v[194:197], v158 offset:33792
	ds_read_b128 v[198:201], v158 offset:34816
	ds_read_b128 v[202:205], v158 offset:35840
	ds_read_b128 v[206:209], v158 offset:36864
	ds_read_b128 v[210:213], v158 offset:37888
	ds_read_b128 v[214:217], v158 offset:38912
	ds_read_b128 v[218:221], v158 offset:39936
	global_load_lds_dwordx4 v[226:227], off
	v_lshl_add_u64 v[226:227], s[40:41], 0, v[130:131]
	s_mov_b32 m0, s52
	s_nop 0
	global_load_lds_dwordx4 v[226:227], off
	s_waitcnt vmcnt(8)
	s_waitcnt lgkmcnt(0)
	s_barrier
	s_setprio 1
	s_waitcnt lgkmcnt(0)
	v_mfma_f32_16x16x32_bf16 v[126:129], v[140:143], v[190:193], v[126:129]
	v_mfma_f32_16x16x32_bf16 v[122:125], v[148:151], v[190:193], v[122:125]
	v_mfma_f32_16x16x32_bf16 v[110:113], v[140:143], v[198:201], v[110:113]
	v_mfma_f32_16x16x32_bf16 v[106:109], v[148:151], v[198:201], v[106:109]
	v_mfma_f32_16x16x32_bf16 v[94:97], v[140:143], v[206:209], v[94:97]
	v_mfma_f32_16x16x32_bf16 v[90:93], v[148:151], v[206:209], v[90:93]
	v_mfma_f32_16x16x32_bf16 v[78:81], v[140:143], v[214:217], v[78:81]
	v_mfma_f32_16x16x32_bf16 v[74:77], v[148:151], v[214:217], v[74:77]
	v_mfma_f32_16x16x32_bf16 v[126:129], v[144:147], v[194:197], v[126:129]
	v_mfma_f32_16x16x32_bf16 v[122:125], v[164:167], v[194:197], v[122:125]
	v_mfma_f32_16x16x32_bf16 v[110:113], v[144:147], v[202:205], v[110:113]
	v_mfma_f32_16x16x32_bf16 v[106:109], v[164:167], v[202:205], v[106:109]
	v_mfma_f32_16x16x32_bf16 v[94:97], v[144:147], v[210:213], v[94:97]
	v_mfma_f32_16x16x32_bf16 v[90:93], v[164:167], v[210:213], v[90:93]
	v_mfma_f32_16x16x32_bf16 v[78:81], v[144:147], v[218:221], v[78:81]
	v_mfma_f32_16x16x32_bf16 v[74:77], v[164:167], v[218:221], v[74:77]
	s_setprio 0
	s_setprio 1
	v_mfma_f32_16x16x32_bf16 v[118:121], v[168:171], v[190:193], v[118:121]
	v_mfma_f32_16x16x32_bf16 v[114:117], v[182:185], v[190:193], v[114:117]
	v_mfma_f32_16x16x32_bf16 v[102:105], v[168:171], v[198:201], v[102:105]
	v_mfma_f32_16x16x32_bf16 v[98:101], v[182:185], v[198:201], v[98:101]
	v_mfma_f32_16x16x32_bf16 v[86:89], v[168:171], v[206:209], v[86:89]
	v_mfma_f32_16x16x32_bf16 v[82:85], v[182:185], v[206:209], v[82:85]
	v_mfma_f32_16x16x32_bf16 v[70:73], v[168:171], v[214:217], v[70:73]
	v_mfma_f32_16x16x32_bf16 v[66:69], v[182:185], v[214:217], v[66:69]
	v_mfma_f32_16x16x32_bf16 v[118:121], v[178:181], v[194:197], v[118:121]
	v_mfma_f32_16x16x32_bf16 v[114:117], v[186:189], v[194:197], v[114:117]
	v_mfma_f32_16x16x32_bf16 v[102:105], v[178:181], v[202:205], v[102:105]
	v_mfma_f32_16x16x32_bf16 v[98:101], v[186:189], v[202:205], v[98:101]
	v_mfma_f32_16x16x32_bf16 v[86:89], v[178:181], v[210:213], v[86:89]
	v_mfma_f32_16x16x32_bf16 v[82:85], v[186:189], v[210:213], v[82:85]
	v_mfma_f32_16x16x32_bf16 v[70:73], v[178:181], v[218:221], v[70:73]
	v_mfma_f32_16x16x32_bf16 v[66:69], v[186:189], v[218:221], v[66:69]
	s_setprio 0
	s_barrier
	s_add_i32 s40, s62, s48
	v_lshl_add_u64 v[152:153], v[152:153], 0, s[20:21]
	s_mov_b32 m0, s40
	ds_read_b128 v[190:193], v158 offset:49152
	ds_read_b128 v[194:197], v158 offset:50176
	ds_read_b128 v[198:201], v158 offset:51200
	ds_read_b128 v[202:205], v158 offset:52224
	ds_read_b128 v[206:209], v158 offset:53248
	ds_read_b128 v[210:213], v158 offset:54272
	ds_read_b128 v[214:217], v158 offset:55296
	ds_read_b128 v[218:221], v158 offset:56320
	global_load_lds_dwordx4 v[152:153], off
	s_add_i32 m0, s40, 0x2000
	s_add_u32 s40, s44, 0x40080
	v_lshl_add_u64 v[152:153], v[172:173], 0, s[20:21]
	s_addc_u32 s41, s45, 0
	s_add_i32 s44, s63, s48
	global_load_lds_dwordx4 v[152:153], off
	v_lshl_add_u64 v[152:153], s[40:41], 0, v[132:133]
	s_mov_b32 m0, s44
	s_nop 0
	global_load_lds_dwordx4 v[152:153], off
	v_lshl_add_u64 v[152:153], s[40:41], 0, v[130:131]
	s_add_i32 m0, s44, 0x2000
	s_nop 0
	global_load_lds_dwordx4 v[152:153], off
	v_lshl_add_u64 v[152:153], v[222:223], 0, s[20:21]
	s_mov_b32 m0, s55
	s_nop 0
	global_load_lds_dwordx4 v[152:153], off
	v_lshl_add_u64 v[152:153], v[224:225], 0, s[20:21]
	s_mov_b32 m0, s56
	s_nop 0
	global_load_lds_dwordx4 v[152:153], off
	s_waitcnt vmcnt(8)
	s_waitcnt lgkmcnt(0)
	s_barrier
	s_setprio 1
	s_waitcnt lgkmcnt(0)
	v_mfma_f32_16x16x32_bf16 v[62:65], v[140:143], v[190:193], v[62:65]
	v_mfma_f32_16x16x32_bf16 v[58:61], v[148:151], v[190:193], v[58:61]
	v_mfma_f32_16x16x32_bf16 v[46:49], v[140:143], v[198:201], v[46:49]
	v_mfma_f32_16x16x32_bf16 v[42:45], v[148:151], v[198:201], v[42:45]
	v_mfma_f32_16x16x32_bf16 v[30:33], v[140:143], v[206:209], v[30:33]
	v_mfma_f32_16x16x32_bf16 v[26:29], v[148:151], v[206:209], v[26:29]
	v_mfma_f32_16x16x32_bf16 v[14:17], v[140:143], v[214:217], v[14:17]
	v_mfma_f32_16x16x32_bf16 v[10:13], v[148:151], v[214:217], v[10:13]
	v_mfma_f32_16x16x32_bf16 v[62:65], v[144:147], v[194:197], v[62:65]
	v_mfma_f32_16x16x32_bf16 v[58:61], v[164:167], v[194:197], v[58:61]
	v_mfma_f32_16x16x32_bf16 v[46:49], v[144:147], v[202:205], v[46:49]
	v_mfma_f32_16x16x32_bf16 v[42:45], v[164:167], v[202:205], v[42:45]
	v_mfma_f32_16x16x32_bf16 v[30:33], v[144:147], v[210:213], v[30:33]
	v_mfma_f32_16x16x32_bf16 v[26:29], v[164:167], v[210:213], v[26:29]
	v_mfma_f32_16x16x32_bf16 v[14:17], v[144:147], v[218:221], v[14:17]
	v_mfma_f32_16x16x32_bf16 v[10:13], v[164:167], v[218:221], v[10:13]
	s_setprio 0
	s_setprio 1
	v_mfma_f32_16x16x32_bf16 v[54:57], v[168:171], v[190:193], v[54:57]
	v_mfma_f32_16x16x32_bf16 v[50:53], v[182:185], v[190:193], v[50:53]
	v_mfma_f32_16x16x32_bf16 v[38:41], v[168:171], v[198:201], v[38:41]
	v_mfma_f32_16x16x32_bf16 v[34:37], v[182:185], v[198:201], v[34:37]
	v_mfma_f32_16x16x32_bf16 v[22:25], v[168:171], v[206:209], v[22:25]
	v_mfma_f32_16x16x32_bf16 v[18:21], v[182:185], v[206:209], v[18:21]
	v_mfma_f32_16x16x32_bf16 v[6:9], v[168:171], v[214:217], v[6:9]
	v_mfma_f32_16x16x32_bf16 v[2:5], v[182:185], v[214:217], v[2:5]
	v_mfma_f32_16x16x32_bf16 v[54:57], v[178:181], v[194:197], v[54:57]
	v_mfma_f32_16x16x32_bf16 v[50:53], v[186:189], v[194:197], v[50:53]
	v_mfma_f32_16x16x32_bf16 v[38:41], v[178:181], v[202:205], v[38:41]
	v_mfma_f32_16x16x32_bf16 v[34:37], v[186:189], v[202:205], v[34:37]
	v_mfma_f32_16x16x32_bf16 v[22:25], v[178:181], v[210:213], v[22:25]
	v_mfma_f32_16x16x32_bf16 v[18:21], v[186:189], v[210:213], v[18:21]
	v_mfma_f32_16x16x32_bf16 v[6:9], v[178:181], v[218:221], v[6:9]
	v_mfma_f32_16x16x32_bf16 v[2:5], v[186:189], v[218:221], v[2:5]
	s_setprio 0
	s_barrier
	s_add_i32 s61, s61, 2
	s_add_u32 s35, s35, 0x100
	s_addc_u32 s39, s39, 0
	s_cmp_gt_u32 s61, 13
	s_mov_b64 s[40:41], s[42:43]
	s_cbranch_scc0 .LBB0_405
	s_branch .Lpeel_exit_405
	.p2alignl 6, 3212836864

.LBB0_1028:
	s_cmp_gt_u32 s27, 2
	s_cselect_b64 s[18:19], -1, 0
	s_cmp_lt_u32 s27, 3
	s_mov_b64 s[20:21], s[6:7]
	s_mov_b64 s[22:23], s[0:1]
	s_cselect_b32 s0, 0x400, 0
	s_add_u32 s6, s20, s0
	s_addc_u32 s7, s21, 0
	s_add_u32 s0, s22, s0
	s_addc_u32 s1, s23, 0
	s_add_u32 s20, s20, 0x80080
	s_addc_u32 s21, s21, 0
	s_add_u32 s44, s22, 0x100
	s_addc_u32 s45, s23, 0
	s_mov_b32 s46, -2
	.p2alignl 6, 3212836864

.LBB0_1134:
	s_ashr_i32 s29, s28, 31
	s_lshl_b64 s[30:31], s[28:29], 19
	s_add_u32 s30, s3, s30
	s_addc_u32 s31, s14, s31
	s_and_b64 s[34:35], s[0:1], exec
	s_cselect_b32 s29, s31, s39
	s_cselect_b32 s57, s30, s38
	s_ashr_i32 s27, s26, 31
	s_lshl_b64 s[34:35], s[26:27], 19
	s_add_u32 s34, s15, s34
	s_addc_u32 s35, s16, s35
	s_and_b64 s[42:43], s[0:1], exec
	s_cselect_b32 s27, s35, s41
	s_cselect_b32 s58, s34, s40
	s_add_u32 s59, s40, 0x100
	s_addc_u32 s60, s41, 0
	s_mov_b32 s61, -2
	ds_read_b128 v[146:149], v156
	ds_read_b128 v[150:153], v156 offset:1024
	ds_read_b128 v[160:163], v156 offset:2048
	ds_read_b128 v[164:167], v156 offset:3072
	ds_read_b128 v[168:171], v157
	ds_read_b128 v[178:181], v157 offset:1024
	ds_read_b128 v[182:185], v157 offset:2048
	ds_read_b128 v[186:189], v157 offset:3072
	s_add_u32 s40, s38, 0x100
	s_addc_u32 s41, s39, 0
	s_cmp_eq_u32 s61, 12
	s_cselect_b32 s45, s29, s41
	s_cselect_b32 s44, s57, s40
	s_cselect_b32 s43, s27, s60
	s_cselect_b32 s42, s58, s59
	v_lshl_add_u64 v[172:173], s[38:39], 0, v[138:139]
	s_add_i32 m0, s37, 0xc000
	ds_read_b128 v[190:193], v158
	ds_read_b128 v[194:197], v158 offset:1024
	ds_read_b128 v[198:201], v158 offset:2048
	ds_read_b128 v[202:205], v158 offset:3072
	ds_read_b128 v[206:209], v158 offset:4096
	ds_read_b128 v[210:213], v158 offset:5120
	ds_read_b128 v[214:217], v158 offset:6144
	ds_read_b128 v[218:221], v158 offset:7168
	global_load_lds_dwordx4 v[172:173], off
	v_lshl_add_u64 v[172:173], s[38:39], 0, v[140:141]
	s_add_i32 m0, s37, 0xe000
	s_nop 0
	global_load_lds_dwordx4 v[172:173], off
	s_waitcnt vmcnt(8)
	s_waitcnt lgkmcnt(0)
	s_barrier
	s_setprio 1
	s_waitcnt lgkmcnt(0)
	v_mfma_f32_16x16x32_bf16 v[126:129], v[146:149], v[190:193], 0
	v_mfma_f32_16x16x32_bf16 v[122:125], v[160:163], v[190:193], 0
	v_mfma_f32_16x16x32_bf16 v[110:113], v[146:149], v[198:201], 0
	v_mfma_f32_16x16x32_bf16 v[106:109], v[160:163], v[198:201], 0
	v_mfma_f32_16x16x32_bf16 v[94:97], v[146:149], v[206:209], 0
	v_mfma_f32_16x16x32_bf16 v[90:93], v[160:163], v[206:209], 0
	v_mfma_f32_16x16x32_bf16 v[78:81], v[146:149], v[214:217], 0
	v_mfma_f32_16x16x32_bf16 v[74:77], v[160:163], v[214:217], 0
	v_mfma_f32_16x16x32_bf16 v[126:129], v[150:153], v[194:197], v[126:129]
	v_mfma_f32_16x16x32_bf16 v[122:125], v[164:167], v[194:197], v[122:125]
	v_mfma_f32_16x16x32_bf16 v[110:113], v[150:153], v[202:205], v[110:113]
	v_mfma_f32_16x16x32_bf16 v[106:109], v[164:167], v[202:205], v[106:109]
	v_mfma_f32_16x16x32_bf16 v[94:97], v[150:153], v[210:213], v[94:97]
	v_mfma_f32_16x16x32_bf16 v[90:93], v[164:167], v[210:213], v[90:93]
	v_mfma_f32_16x16x32_bf16 v[78:81], v[150:153], v[218:221], v[78:81]
	v_mfma_f32_16x16x32_bf16 v[74:77], v[164:167], v[218:221], v[74:77]
	s_setprio 0
	s_setprio 1
	v_mfma_f32_16x16x32_bf16 v[118:121], v[168:171], v[190:193], 0
	v_mfma_f32_16x16x32_bf16 v[114:117], v[182:185], v[190:193], 0
	v_mfma_f32_16x16x32_bf16 v[102:105], v[168:171], v[198:201], 0
	v_mfma_f32_16x16x32_bf16 v[98:101], v[182:185], v[198:201], 0
	v_mfma_f32_16x16x32_bf16 v[86:89], v[168:171], v[206:209], 0
	v_mfma_f32_16x16x32_bf16 v[82:85], v[182:185], v[206:209], 0
	v_mfma_f32_16x16x32_bf16 v[70:73], v[168:171], v[214:217], 0
	v_mfma_f32_16x16x32_bf16 v[66:69], v[182:185], v[214:217], 0
	v_mfma_f32_16x16x32_bf16 v[118:121], v[178:181], v[194:197], v[118:121]
	v_mfma_f32_16x16x32_bf16 v[114:117], v[186:189], v[194:197], v[114:117]
	v_mfma_f32_16x16x32_bf16 v[102:105], v[178:181], v[202:205], v[102:105]
	v_mfma_f32_16x16x32_bf16 v[98:101], v[186:189], v[202:205], v[98:101]
	v_mfma_f32_16x16x32_bf16 v[86:89], v[178:181], v[210:213], v[86:89]
	v_mfma_f32_16x16x32_bf16 v[82:85], v[186:189], v[210:213], v[82:85]
	v_mfma_f32_16x16x32_bf16 v[70:73], v[178:181], v[218:221], v[70:73]
	v_mfma_f32_16x16x32_bf16 v[66:69], v[186:189], v[218:221], v[66:69]
	s_setprio 0
	s_barrier
	s_add_i32 s38, s54, s46
	v_lshl_add_u64 v[172:173], s[42:43], 0, v[132:133]
	s_mov_b32 m0, s38
	ds_read_b128 v[190:193], v158 offset:16384
	ds_read_b128 v[194:197], v158 offset:17408
	ds_read_b128 v[198:201], v158 offset:18432
	ds_read_b128 v[202:205], v158 offset:19456
	ds_read_b128 v[206:209], v158 offset:20480
	ds_read_b128 v[210:213], v158 offset:21504
	ds_read_b128 v[214:217], v158 offset:22528
	ds_read_b128 v[218:221], v158 offset:23552
	global_load_lds_dwordx4 v[172:173], off
	s_add_i32 m0, s38, 0x2000
	s_add_u32 s38, s42, 0x40000
	v_lshl_add_u64 v[222:223], s[42:43], 0, v[136:137]
	s_addc_u32 s39, s43, 0
	s_add_i32 s62, s55, s46
	global_load_lds_dwordx4 v[222:223], off
	v_lshl_add_u64 v[224:225], s[38:39], 0, v[132:133]
	s_mov_b32 m0, s62
	v_lshl_add_u64 v[226:227], s[44:45], 0, v[134:135]
	global_load_lds_dwordx4 v[224:225], off
	v_lshl_add_u64 v[224:225], s[38:39], 0, v[136:137]
	s_add_i32 m0, s62, 0x2000
	s_nop 0
	global_load_lds_dwordx4 v[224:225], off
	v_lshl_add_u64 v[224:225], s[44:45], 0, v[130:131]
	s_mov_b32 m0, s37
	s_nop 0
	global_load_lds_dwordx4 v[224:225], off
	s_mov_b32 m0, s47
	s_nop 0
	global_load_lds_dwordx4 v[226:227], off
	s_waitcnt vmcnt(8)
	s_waitcnt lgkmcnt(0)
	s_barrier
	s_setprio 1
	s_waitcnt lgkmcnt(0)
	v_mfma_f32_16x16x32_bf16 v[62:65], v[146:149], v[190:193], 0
	v_mfma_f32_16x16x32_bf16 v[58:61], v[160:163], v[190:193], 0
	v_mfma_f32_16x16x32_bf16 v[46:49], v[146:149], v[198:201], 0
	v_mfma_f32_16x16x32_bf16 v[42:45], v[160:163], v[198:201], 0
	v_mfma_f32_16x16x32_bf16 v[30:33], v[146:149], v[206:209], 0
	v_mfma_f32_16x16x32_bf16 v[26:29], v[160:163], v[206:209], 0
	v_mfma_f32_16x16x32_bf16 v[14:17], v[146:149], v[214:217], 0
	v_mfma_f32_16x16x32_bf16 v[10:13], v[160:163], v[214:217], 0
	v_mfma_f32_16x16x32_bf16 v[62:65], v[150:153], v[194:197], v[62:65]
	v_mfma_f32_16x16x32_bf16 v[58:61], v[164:167], v[194:197], v[58:61]
	v_mfma_f32_16x16x32_bf16 v[46:49], v[150:153], v[202:205], v[46:49]
	v_mfma_f32_16x16x32_bf16 v[42:45], v[164:167], v[202:205], v[42:45]
	v_mfma_f32_16x16x32_bf16 v[30:33], v[150:153], v[210:213], v[30:33]
	v_mfma_f32_16x16x32_bf16 v[26:29], v[164:167], v[210:213], v[26:29]
	v_mfma_f32_16x16x32_bf16 v[14:17], v[150:153], v[218:221], v[14:17]
	v_mfma_f32_16x16x32_bf16 v[10:13], v[164:167], v[218:221], v[10:13]
	s_setprio 0
	s_setprio 1
	v_mfma_f32_16x16x32_bf16 v[54:57], v[168:171], v[190:193], 0
	v_mfma_f32_16x16x32_bf16 v[50:53], v[182:185], v[190:193], 0
	v_mfma_f32_16x16x32_bf16 v[38:41], v[168:171], v[198:201], 0
	v_mfma_f32_16x16x32_bf16 v[34:37], v[182:185], v[198:201], 0
	v_mfma_f32_16x16x32_bf16 v[22:25], v[168:171], v[206:209], 0
	v_mfma_f32_16x16x32_bf16 v[18:21], v[182:185], v[206:209], 0
	v_mfma_f32_16x16x32_bf16 v[6:9], v[168:171], v[214:217], 0
	v_mfma_f32_16x16x32_bf16 v[2:5], v[182:185], v[214:217], 0
	v_mfma_f32_16x16x32_bf16 v[54:57], v[178:181], v[194:197], v[54:57]
	v_mfma_f32_16x16x32_bf16 v[50:53], v[186:189], v[194:197], v[50:53]
	v_mfma_f32_16x16x32_bf16 v[38:41], v[178:181], v[202:205], v[38:41]
	v_mfma_f32_16x16x32_bf16 v[34:37], v[186:189], v[202:205], v[34:37]
	v_mfma_f32_16x16x32_bf16 v[22:25], v[178:181], v[210:213], v[22:25]
	v_mfma_f32_16x16x32_bf16 v[18:21], v[186:189], v[210:213], v[18:21]
	v_mfma_f32_16x16x32_bf16 v[6:9], v[178:181], v[218:221], v[6:9]
	v_mfma_f32_16x16x32_bf16 v[2:5], v[186:189], v[218:221], v[2:5]
	s_setprio 0
	s_barrier
	s_add_i32 s62, 0, 0x18000
	v_add_u32_e32 v159, s62, v154
	s_add_i32 s63, 0, 0x1c000
	ds_read_b128 v[146:149], v159
	ds_read_b128 v[150:153], v159 offset:1024
	ds_read_b128 v[160:163], v159 offset:2048
	ds_read_b128 v[164:167], v159 offset:3072
	v_add_u32_e32 v159, s63, v154
	ds_read_b128 v[168:171], v159
	ds_read_b128 v[178:181], v159 offset:1024
	ds_read_b128 v[182:185], v159 offset:2048
	ds_read_b128 v[186:189], v159 offset:3072
	s_add_u32 s38, s44, 0x40000
	s_addc_u32 s39, s45, 0
	s_mov_b32 m0, s48
	v_lshl_add_u64 v[228:229], s[38:39], 0, v[130:131]
	ds_read_b128 v[190:193], v158 offset:32768
	ds_read_b128 v[194:197], v158 offset:33792
	ds_read_b128 v[198:201], v158 offset:34816
	ds_read_b128 v[202:205], v158 offset:35840
	ds_read_b128 v[206:209], v158 offset:36864
	ds_read_b128 v[210:213], v158 offset:37888
	ds_read_b128 v[214:217], v158 offset:38912
	ds_read_b128 v[218:221], v158 offset:39936
	global_load_lds_dwordx4 v[228:229], off
	v_lshl_add_u64 v[228:229], s[38:39], 0, v[134:135]
	s_mov_b32 m0, s49
	s_nop 0
	global_load_lds_dwordx4 v[228:229], off
	s_waitcnt vmcnt(8)
	s_waitcnt lgkmcnt(0)
	s_barrier
	s_setprio 1
	s_waitcnt lgkmcnt(0)
	v_mfma_f32_16x16x32_bf16 v[126:129], v[146:149], v[190:193], v[126:129]
	v_mfma_f32_16x16x32_bf16 v[122:125], v[160:163], v[190:193], v[122:125]
	v_mfma_f32_16x16x32_bf16 v[110:113], v[146:149], v[198:201], v[110:113]
	v_mfma_f32_16x16x32_bf16 v[106:109], v[160:163], v[198:201], v[106:109]
	v_mfma_f32_16x16x32_bf16 v[94:97], v[146:149], v[206:209], v[94:97]
	v_mfma_f32_16x16x32_bf16 v[90:93], v[160:163], v[206:209], v[90:93]
	v_mfma_f32_16x16x32_bf16 v[78:81], v[146:149], v[214:217], v[78:81]
	v_mfma_f32_16x16x32_bf16 v[74:77], v[160:163], v[214:217], v[74:77]
	v_mfma_f32_16x16x32_bf16 v[126:129], v[150:153], v[194:197], v[126:129]
	v_mfma_f32_16x16x32_bf16 v[122:125], v[164:167], v[194:197], v[122:125]
	v_mfma_f32_16x16x32_bf16 v[110:113], v[150:153], v[202:205], v[110:113]
	v_mfma_f32_16x16x32_bf16 v[106:109], v[164:167], v[202:205], v[106:109]
	v_mfma_f32_16x16x32_bf16 v[94:97], v[150:153], v[210:213], v[94:97]
	v_mfma_f32_16x16x32_bf16 v[90:93], v[164:167], v[210:213], v[90:93]
	v_mfma_f32_16x16x32_bf16 v[78:81], v[150:153], v[218:221], v[78:81]
	v_mfma_f32_16x16x32_bf16 v[74:77], v[164:167], v[218:221], v[74:77]
	s_setprio 0
	s_setprio 1
	v_mfma_f32_16x16x32_bf16 v[118:121], v[168:171], v[190:193], v[118:121]
	v_mfma_f32_16x16x32_bf16 v[114:117], v[182:185], v[190:193], v[114:117]
	v_mfma_f32_16x16x32_bf16 v[102:105], v[168:171], v[198:201], v[102:105]
	v_mfma_f32_16x16x32_bf16 v[98:101], v[182:185], v[198:201], v[98:101]
	v_mfma_f32_16x16x32_bf16 v[86:89], v[168:171], v[206:209], v[86:89]
	v_mfma_f32_16x16x32_bf16 v[82:85], v[182:185], v[206:209], v[82:85]
	v_mfma_f32_16x16x32_bf16 v[70:73], v[168:171], v[214:217], v[70:73]
	v_mfma_f32_16x16x32_bf16 v[66:69], v[182:185], v[214:217], v[66:69]
	v_mfma_f32_16x16x32_bf16 v[118:121], v[178:181], v[194:197], v[118:121]
	v_mfma_f32_16x16x32_bf16 v[114:117], v[186:189], v[194:197], v[114:117]
	v_mfma_f32_16x16x32_bf16 v[102:105], v[178:181], v[202:205], v[102:105]
	v_mfma_f32_16x16x32_bf16 v[98:101], v[186:189], v[202:205], v[98:101]
	v_mfma_f32_16x16x32_bf16 v[86:89], v[178:181], v[210:213], v[86:89]
	v_mfma_f32_16x16x32_bf16 v[82:85], v[186:189], v[210:213], v[82:85]
	v_mfma_f32_16x16x32_bf16 v[70:73], v[178:181], v[218:221], v[70:73]
	v_mfma_f32_16x16x32_bf16 v[66:69], v[186:189], v[218:221], v[66:69]
	s_setprio 0
	s_barrier
	s_add_i32 s38, s62, s46
	v_lshl_add_u64 v[172:173], v[172:173], 0, s[12:13]
	s_mov_b32 m0, s38
	ds_read_b128 v[190:193], v158 offset:49152
	ds_read_b128 v[194:197], v158 offset:50176
	ds_read_b128 v[198:201], v158 offset:51200
	ds_read_b128 v[202:205], v158 offset:52224
	ds_read_b128 v[206:209], v158 offset:53248
	ds_read_b128 v[210:213], v158 offset:54272
	ds_read_b128 v[214:217], v158 offset:55296
	ds_read_b128 v[218:221], v158 offset:56320
	global_load_lds_dwordx4 v[172:173], off
	s_add_i32 m0, s38, 0x2000
	s_add_u32 s38, s42, 0x40080
	v_lshl_add_u64 v[172:173], v[222:223], 0, s[12:13]
	s_addc_u32 s39, s43, 0
	s_add_i32 s42, s63, s46
	global_load_lds_dwordx4 v[172:173], off
	v_lshl_add_u64 v[172:173], s[38:39], 0, v[132:133]
	s_mov_b32 m0, s42
	s_nop 0
	global_load_lds_dwordx4 v[172:173], off
	v_lshl_add_u64 v[172:173], s[38:39], 0, v[136:137]
	s_add_i32 m0, s42, 0x2000
	s_nop 0
	global_load_lds_dwordx4 v[172:173], off
	v_lshl_add_u64 v[172:173], v[224:225], 0, s[12:13]
	s_mov_b32 m0, s51
	s_nop 0
	global_load_lds_dwordx4 v[172:173], off
	v_lshl_add_u64 v[172:173], v[226:227], 0, s[12:13]
	s_mov_b32 m0, s52
	s_nop 0
	global_load_lds_dwordx4 v[172:173], off
	s_waitcnt vmcnt(8)
	s_waitcnt lgkmcnt(0)
	s_barrier
	s_setprio 1
	s_waitcnt lgkmcnt(0)
	v_mfma_f32_16x16x32_bf16 v[62:65], v[146:149], v[190:193], v[62:65]
	v_mfma_f32_16x16x32_bf16 v[58:61], v[160:163], v[190:193], v[58:61]
	v_mfma_f32_16x16x32_bf16 v[46:49], v[146:149], v[198:201], v[46:49]
	v_mfma_f32_16x16x32_bf16 v[42:45], v[160:163], v[198:201], v[42:45]
	v_mfma_f32_16x16x32_bf16 v[30:33], v[146:149], v[206:209], v[30:33]
	v_mfma_f32_16x16x32_bf16 v[26:29], v[160:163], v[206:209], v[26:29]
	v_mfma_f32_16x16x32_bf16 v[14:17], v[146:149], v[214:217], v[14:17]
	v_mfma_f32_16x16x32_bf16 v[10:13], v[160:163], v[214:217], v[10:13]
	v_mfma_f32_16x16x32_bf16 v[62:65], v[150:153], v[194:197], v[62:65]
	v_mfma_f32_16x16x32_bf16 v[58:61], v[164:167], v[194:197], v[58:61]
	v_mfma_f32_16x16x32_bf16 v[46:49], v[150:153], v[202:205], v[46:49]
	v_mfma_f32_16x16x32_bf16 v[42:45], v[164:167], v[202:205], v[42:45]
	v_mfma_f32_16x16x32_bf16 v[30:33], v[150:153], v[210:213], v[30:33]
	v_mfma_f32_16x16x32_bf16 v[26:29], v[164:167], v[210:213], v[26:29]
	v_mfma_f32_16x16x32_bf16 v[14:17], v[150:153], v[218:221], v[14:17]
	v_mfma_f32_16x16x32_bf16 v[10:13], v[164:167], v[218:221], v[10:13]
	s_setprio 0
	s_setprio 1
	v_mfma_f32_16x16x32_bf16 v[54:57], v[168:171], v[190:193], v[54:57]
	v_mfma_f32_16x16x32_bf16 v[50:53], v[182:185], v[190:193], v[50:53]
	v_mfma_f32_16x16x32_bf16 v[38:41], v[168:171], v[198:201], v[38:41]
	v_mfma_f32_16x16x32_bf16 v[34:37], v[182:185], v[198:201], v[34:37]
	v_mfma_f32_16x16x32_bf16 v[22:25], v[168:171], v[206:209], v[22:25]
	v_mfma_f32_16x16x32_bf16 v[18:21], v[182:185], v[206:209], v[18:21]
	v_mfma_f32_16x16x32_bf16 v[6:9], v[168:171], v[214:217], v[6:9]
	v_mfma_f32_16x16x32_bf16 v[2:5], v[182:185], v[214:217], v[2:5]
	v_mfma_f32_16x16x32_bf16 v[54:57], v[178:181], v[194:197], v[54:57]
	v_mfma_f32_16x16x32_bf16 v[50:53], v[186:189], v[194:197], v[50:53]
	v_mfma_f32_16x16x32_bf16 v[38:41], v[178:181], v[202:205], v[38:41]
	v_mfma_f32_16x16x32_bf16 v[34:37], v[186:189], v[202:205], v[34:37]
	v_mfma_f32_16x16x32_bf16 v[22:25], v[178:181], v[210:213], v[22:25]
	v_mfma_f32_16x16x32_bf16 v[18:21], v[186:189], v[210:213], v[18:21]
	v_mfma_f32_16x16x32_bf16 v[6:9], v[178:181], v[218:221], v[6:9]
	v_mfma_f32_16x16x32_bf16 v[2:5], v[186:189], v[218:221], v[2:5]
	s_setprio 0
	s_barrier
	s_add_i32 s61, s61, 2
	s_add_u32 s59, s59, 0x100
	s_addc_u32 s60, s60, 0
	s_cmp_gt_u32 s61, 13
	s_mov_b64 s[38:39], s[40:41]
	s_cbranch_scc0 .LBB0_1135
	s_branch .Lpeel_exit_1135
	.p2alignl 6, 3212836864

.LBB0_1223:
	s_ashr_i32 s27, s26, 31
	s_lshl_b64 s[28:29], s[26:27], 19
	s_add_u32 s28, s3, s28
	s_addc_u32 s29, s14, s29
	s_and_b64 s[30:31], s[4:5], exec
	s_cselect_b32 s27, s29, s37
	s_cselect_b32 s35, s28, s36
	s_ashr_i32 s25, s24, 31
	s_lshl_b64 s[30:31], s[24:25], 19
	s_add_u32 s30, s15, s30
	s_addc_u32 s31, s16, s31
	s_and_b64 s[40:41], s[4:5], exec
	s_cselect_b32 s25, s31, s39
	s_cselect_b32 s56, s30, s38
	s_add_u32 s57, s38, 0x100
	s_addc_u32 s58, s39, 0
	s_mov_b32 s59, -2
	s_waitcnt lgkmcnt(0)
	ds_read_b128 v[146:149], v154
	ds_read_b128 v[158:161], v154 offset:1024
	ds_read_b128 v[162:165], v154 offset:2048
	ds_read_b128 v[166:169], v154 offset:3072
	ds_read_b128 v[170:173], v155
	ds_read_b128 v[178:181], v155 offset:1024
	ds_read_b128 v[182:185], v155 offset:2048
	ds_read_b128 v[186:189], v155 offset:3072
	s_add_u32 s38, s36, 0x100
	s_addc_u32 s39, s37, 0
	s_cmp_eq_u32 s59, 12
	s_cselect_b32 s43, s27, s39
	s_cselect_b32 s42, s35, s38
	s_cselect_b32 s41, s25, s58
	s_cselect_b32 s40, s56, s57
	v_lshl_add_u64 v[150:151], s[36:37], 0, v[138:139]
	s_add_i32 m0, s44, 0xc000
	ds_read_b128 v[190:193], v156
	ds_read_b128 v[194:197], v156 offset:1024
	ds_read_b128 v[198:201], v156 offset:2048
	ds_read_b128 v[202:205], v156 offset:3072
	ds_read_b128 v[206:209], v156 offset:4096
	ds_read_b128 v[210:213], v156 offset:5120
	ds_read_b128 v[214:217], v156 offset:6144
	ds_read_b128 v[218:221], v156 offset:7168
	global_load_lds_dwordx4 v[150:151], off
	v_lshl_add_u64 v[150:151], s[36:37], 0, v[140:141]
	s_add_i32 m0, s44, 0xe000
	s_nop 0
	global_load_lds_dwordx4 v[150:151], off
	s_waitcnt vmcnt(8)
	s_waitcnt lgkmcnt(0)
	s_barrier
	s_setprio 1
	s_waitcnt lgkmcnt(0)
	v_mfma_f32_16x16x32_bf16 v[126:129], v[146:149], v[190:193], 0
	v_mfma_f32_16x16x32_bf16 v[122:125], v[162:165], v[190:193], 0
	v_mfma_f32_16x16x32_bf16 v[110:113], v[146:149], v[198:201], 0
	v_mfma_f32_16x16x32_bf16 v[106:109], v[162:165], v[198:201], 0
	v_mfma_f32_16x16x32_bf16 v[94:97], v[146:149], v[206:209], 0
	v_mfma_f32_16x16x32_bf16 v[90:93], v[162:165], v[206:209], 0
	v_mfma_f32_16x16x32_bf16 v[78:81], v[146:149], v[214:217], 0
	v_mfma_f32_16x16x32_bf16 v[74:77], v[162:165], v[214:217], 0
	v_mfma_f32_16x16x32_bf16 v[126:129], v[158:161], v[194:197], v[126:129]
	v_mfma_f32_16x16x32_bf16 v[122:125], v[166:169], v[194:197], v[122:125]
	v_mfma_f32_16x16x32_bf16 v[110:113], v[158:161], v[202:205], v[110:113]
	v_mfma_f32_16x16x32_bf16 v[106:109], v[166:169], v[202:205], v[106:109]
	v_mfma_f32_16x16x32_bf16 v[94:97], v[158:161], v[210:213], v[94:97]
	v_mfma_f32_16x16x32_bf16 v[90:93], v[166:169], v[210:213], v[90:93]
	v_mfma_f32_16x16x32_bf16 v[78:81], v[158:161], v[218:221], v[78:81]
	v_mfma_f32_16x16x32_bf16 v[74:77], v[166:169], v[218:221], v[74:77]
	s_setprio 0
	s_setprio 1
	v_mfma_f32_16x16x32_bf16 v[118:121], v[170:173], v[190:193], 0
	v_mfma_f32_16x16x32_bf16 v[114:117], v[182:185], v[190:193], 0
	v_mfma_f32_16x16x32_bf16 v[102:105], v[170:173], v[198:201], 0
	v_mfma_f32_16x16x32_bf16 v[98:101], v[182:185], v[198:201], 0
	v_mfma_f32_16x16x32_bf16 v[86:89], v[170:173], v[206:209], 0
	v_mfma_f32_16x16x32_bf16 v[82:85], v[182:185], v[206:209], 0
	v_mfma_f32_16x16x32_bf16 v[70:73], v[170:173], v[214:217], 0
	v_mfma_f32_16x16x32_bf16 v[66:69], v[182:185], v[214:217], 0
	v_mfma_f32_16x16x32_bf16 v[118:121], v[178:181], v[194:197], v[118:121]
	v_mfma_f32_16x16x32_bf16 v[114:117], v[186:189], v[194:197], v[114:117]
	v_mfma_f32_16x16x32_bf16 v[102:105], v[178:181], v[202:205], v[102:105]
	v_mfma_f32_16x16x32_bf16 v[98:101], v[186:189], v[202:205], v[98:101]
	v_mfma_f32_16x16x32_bf16 v[86:89], v[178:181], v[210:213], v[86:89]
	v_mfma_f32_16x16x32_bf16 v[82:85], v[186:189], v[210:213], v[82:85]
	v_mfma_f32_16x16x32_bf16 v[70:73], v[178:181], v[218:221], v[70:73]
	v_mfma_f32_16x16x32_bf16 v[66:69], v[186:189], v[218:221], v[66:69]
	s_setprio 0
	s_barrier
	s_add_i32 s36, s53, s17
	v_lshl_add_u64 v[150:151], s[40:41], 0, v[132:133]
	s_mov_b32 m0, s36
	ds_read_b128 v[190:193], v156 offset:16384
	ds_read_b128 v[194:197], v156 offset:17408
	ds_read_b128 v[198:201], v156 offset:18432
	ds_read_b128 v[202:205], v156 offset:19456
	ds_read_b128 v[206:209], v156 offset:20480
	ds_read_b128 v[210:213], v156 offset:21504
	ds_read_b128 v[214:217], v156 offset:22528
	ds_read_b128 v[218:221], v156 offset:23552
	global_load_lds_dwordx4 v[150:151], off
	s_add_i32 m0, s36, 0x2000
	s_add_u32 s36, s40, 0x40000
	v_lshl_add_u64 v[222:223], s[40:41], 0, v[136:137]
	s_addc_u32 s37, s41, 0
	s_add_i32 s60, s54, s17
	global_load_lds_dwordx4 v[222:223], off
	v_lshl_add_u64 v[224:225], s[36:37], 0, v[132:133]
	s_mov_b32 m0, s60
	v_lshl_add_u64 v[226:227], s[42:43], 0, v[134:135]
	global_load_lds_dwordx4 v[224:225], off
	v_lshl_add_u64 v[224:225], s[36:37], 0, v[136:137]
	s_add_i32 m0, s60, 0x2000
	s_nop 0
	global_load_lds_dwordx4 v[224:225], off
	v_lshl_add_u64 v[224:225], s[42:43], 0, v[130:131]
	s_mov_b32 m0, s44
	s_nop 0
	global_load_lds_dwordx4 v[224:225], off
	s_mov_b32 m0, s45
	s_nop 0
	global_load_lds_dwordx4 v[226:227], off
	s_waitcnt vmcnt(8)
	s_waitcnt lgkmcnt(0)
	s_barrier
	s_setprio 1
	s_waitcnt lgkmcnt(0)
	v_mfma_f32_16x16x32_bf16 v[62:65], v[146:149], v[190:193], 0
	v_mfma_f32_16x16x32_bf16 v[58:61], v[162:165], v[190:193], 0
	v_mfma_f32_16x16x32_bf16 v[46:49], v[146:149], v[198:201], 0
	v_mfma_f32_16x16x32_bf16 v[42:45], v[162:165], v[198:201], 0
	v_mfma_f32_16x16x32_bf16 v[30:33], v[146:149], v[206:209], 0
	v_mfma_f32_16x16x32_bf16 v[26:29], v[162:165], v[206:209], 0
	v_mfma_f32_16x16x32_bf16 v[14:17], v[146:149], v[214:217], 0
	v_mfma_f32_16x16x32_bf16 v[10:13], v[162:165], v[214:217], 0
	v_mfma_f32_16x16x32_bf16 v[62:65], v[158:161], v[194:197], v[62:65]
	v_mfma_f32_16x16x32_bf16 v[58:61], v[166:169], v[194:197], v[58:61]
	v_mfma_f32_16x16x32_bf16 v[46:49], v[158:161], v[202:205], v[46:49]
	v_mfma_f32_16x16x32_bf16 v[42:45], v[166:169], v[202:205], v[42:45]
	v_mfma_f32_16x16x32_bf16 v[30:33], v[158:161], v[210:213], v[30:33]
	v_mfma_f32_16x16x32_bf16 v[26:29], v[166:169], v[210:213], v[26:29]
	v_mfma_f32_16x16x32_bf16 v[14:17], v[158:161], v[218:221], v[14:17]
	v_mfma_f32_16x16x32_bf16 v[10:13], v[166:169], v[218:221], v[10:13]
	s_setprio 0
	s_setprio 1
	v_mfma_f32_16x16x32_bf16 v[54:57], v[170:173], v[190:193], 0
	v_mfma_f32_16x16x32_bf16 v[50:53], v[182:185], v[190:193], 0
	v_mfma_f32_16x16x32_bf16 v[38:41], v[170:173], v[198:201], 0
	v_mfma_f32_16x16x32_bf16 v[34:37], v[182:185], v[198:201], 0
	v_mfma_f32_16x16x32_bf16 v[22:25], v[170:173], v[206:209], 0
	v_mfma_f32_16x16x32_bf16 v[18:21], v[182:185], v[206:209], 0
	v_mfma_f32_16x16x32_bf16 v[6:9], v[170:173], v[214:217], 0
	v_mfma_f32_16x16x32_bf16 v[2:5], v[182:185], v[214:217], 0
	v_mfma_f32_16x16x32_bf16 v[54:57], v[178:181], v[194:197], v[54:57]
	v_mfma_f32_16x16x32_bf16 v[50:53], v[186:189], v[194:197], v[50:53]
	v_mfma_f32_16x16x32_bf16 v[38:41], v[178:181], v[202:205], v[38:41]
	v_mfma_f32_16x16x32_bf16 v[34:37], v[186:189], v[202:205], v[34:37]
	v_mfma_f32_16x16x32_bf16 v[22:25], v[178:181], v[210:213], v[22:25]
	v_mfma_f32_16x16x32_bf16 v[18:21], v[186:189], v[210:213], v[18:21]
	v_mfma_f32_16x16x32_bf16 v[6:9], v[178:181], v[218:221], v[6:9]
	v_mfma_f32_16x16x32_bf16 v[2:5], v[186:189], v[218:221], v[2:5]
	s_setprio 0
	s_barrier
	s_add_i32 s60, 0, 0x18000
	s_add_i32 s61, 0, 0x1c000
	v_add_u32_e32 v166, s60, v152
	v_add_u32_e32 v177, s61, v152
	ds_read_b128 v[146:149], v166
	ds_read_b128 v[158:161], v166 offset:1024
	ds_read_b128 v[162:165], v166 offset:2048
	ds_read_b128 v[166:169], v166 offset:3072
	ds_read_b128 v[170:173], v177
	ds_read_b128 v[178:181], v177 offset:1024
	ds_read_b128 v[182:185], v177 offset:2048
	ds_read_b128 v[186:189], v177 offset:3072
	s_add_u32 s36, s42, 0x40000
	s_addc_u32 s37, s43, 0
	s_mov_b32 m0, s46
	v_lshl_add_u64 v[228:229], s[36:37], 0, v[130:131]
	ds_read_b128 v[190:193], v156 offset:32768
	ds_read_b128 v[194:197], v156 offset:33792
	ds_read_b128 v[198:201], v156 offset:34816
	ds_read_b128 v[202:205], v156 offset:35840
	ds_read_b128 v[206:209], v156 offset:36864
	ds_read_b128 v[210:213], v156 offset:37888
	ds_read_b128 v[214:217], v156 offset:38912
	ds_read_b128 v[218:221], v156 offset:39936
	global_load_lds_dwordx4 v[228:229], off
	v_lshl_add_u64 v[228:229], s[36:37], 0, v[134:135]
	s_mov_b32 m0, s47
	s_nop 0
	global_load_lds_dwordx4 v[228:229], off
	s_waitcnt vmcnt(8)
	s_waitcnt lgkmcnt(0)
	s_barrier
	s_setprio 1
	s_waitcnt lgkmcnt(0)
	v_mfma_f32_16x16x32_bf16 v[126:129], v[146:149], v[190:193], v[126:129]
	v_mfma_f32_16x16x32_bf16 v[122:125], v[162:165], v[190:193], v[122:125]
	v_mfma_f32_16x16x32_bf16 v[110:113], v[146:149], v[198:201], v[110:113]
	v_mfma_f32_16x16x32_bf16 v[106:109], v[162:165], v[198:201], v[106:109]
	v_mfma_f32_16x16x32_bf16 v[94:97], v[146:149], v[206:209], v[94:97]
	v_mfma_f32_16x16x32_bf16 v[90:93], v[162:165], v[206:209], v[90:93]
	v_mfma_f32_16x16x32_bf16 v[78:81], v[146:149], v[214:217], v[78:81]
	v_mfma_f32_16x16x32_bf16 v[74:77], v[162:165], v[214:217], v[74:77]
	v_mfma_f32_16x16x32_bf16 v[126:129], v[158:161], v[194:197], v[126:129]
	v_mfma_f32_16x16x32_bf16 v[122:125], v[166:169], v[194:197], v[122:125]
	v_mfma_f32_16x16x32_bf16 v[110:113], v[158:161], v[202:205], v[110:113]
	v_mfma_f32_16x16x32_bf16 v[106:109], v[166:169], v[202:205], v[106:109]
	v_mfma_f32_16x16x32_bf16 v[94:97], v[158:161], v[210:213], v[94:97]
	v_mfma_f32_16x16x32_bf16 v[90:93], v[166:169], v[210:213], v[90:93]
	v_mfma_f32_16x16x32_bf16 v[78:81], v[158:161], v[218:221], v[78:81]
	v_mfma_f32_16x16x32_bf16 v[74:77], v[166:169], v[218:221], v[74:77]
	s_setprio 0
	s_setprio 1
	v_mfma_f32_16x16x32_bf16 v[118:121], v[170:173], v[190:193], v[118:121]
	v_mfma_f32_16x16x32_bf16 v[114:117], v[182:185], v[190:193], v[114:117]
	v_mfma_f32_16x16x32_bf16 v[102:105], v[170:173], v[198:201], v[102:105]
	v_mfma_f32_16x16x32_bf16 v[98:101], v[182:185], v[198:201], v[98:101]
	v_mfma_f32_16x16x32_bf16 v[86:89], v[170:173], v[206:209], v[86:89]
	v_mfma_f32_16x16x32_bf16 v[82:85], v[182:185], v[206:209], v[82:85]
	v_mfma_f32_16x16x32_bf16 v[70:73], v[170:173], v[214:217], v[70:73]
	v_mfma_f32_16x16x32_bf16 v[66:69], v[182:185], v[214:217], v[66:69]
	v_mfma_f32_16x16x32_bf16 v[118:121], v[178:181], v[194:197], v[118:121]
	v_mfma_f32_16x16x32_bf16 v[114:117], v[186:189], v[194:197], v[114:117]
	v_mfma_f32_16x16x32_bf16 v[102:105], v[178:181], v[202:205], v[102:105]
	v_mfma_f32_16x16x32_bf16 v[98:101], v[186:189], v[202:205], v[98:101]
	v_mfma_f32_16x16x32_bf16 v[86:89], v[178:181], v[210:213], v[86:89]
	v_mfma_f32_16x16x32_bf16 v[82:85], v[186:189], v[210:213], v[82:85]
	v_mfma_f32_16x16x32_bf16 v[70:73], v[178:181], v[218:221], v[70:73]
	v_mfma_f32_16x16x32_bf16 v[66:69], v[186:189], v[218:221], v[66:69]
	s_setprio 0
	s_barrier
	s_add_i32 s36, s60, s17
	v_lshl_add_u64 v[150:151], v[150:151], 0, s[20:21]
	s_mov_b32 m0, s36
	ds_read_b128 v[190:193], v156 offset:49152
	ds_read_b128 v[194:197], v156 offset:50176
	ds_read_b128 v[198:201], v156 offset:51200
	ds_read_b128 v[202:205], v156 offset:52224
	ds_read_b128 v[206:209], v156 offset:53248
	ds_read_b128 v[210:213], v156 offset:54272
	ds_read_b128 v[214:217], v156 offset:55296
	ds_read_b128 v[218:221], v156 offset:56320
	global_load_lds_dwordx4 v[150:151], off
	s_add_i32 m0, s36, 0x2000
	s_add_u32 s36, s40, 0x40080
	v_lshl_add_u64 v[150:151], v[222:223], 0, s[20:21]
	s_addc_u32 s37, s41, 0
	s_add_i32 s40, s61, s17
	global_load_lds_dwordx4 v[150:151], off
	v_lshl_add_u64 v[150:151], s[36:37], 0, v[132:133]
	s_mov_b32 m0, s40
	s_nop 0
	global_load_lds_dwordx4 v[150:151], off
	v_lshl_add_u64 v[150:151], s[36:37], 0, v[136:137]
	s_add_i32 m0, s40, 0x2000
	s_nop 0
	global_load_lds_dwordx4 v[150:151], off
	v_lshl_add_u64 v[150:151], v[224:225], 0, s[20:21]
	s_mov_b32 m0, s49
	s_nop 0
	global_load_lds_dwordx4 v[150:151], off
	v_lshl_add_u64 v[150:151], v[226:227], 0, s[20:21]
	s_mov_b32 m0, s50
	s_nop 0
	global_load_lds_dwordx4 v[150:151], off
	s_waitcnt vmcnt(8)
	s_waitcnt lgkmcnt(0)
	s_barrier
	s_setprio 1
	s_waitcnt lgkmcnt(0)
	v_mfma_f32_16x16x32_bf16 v[62:65], v[146:149], v[190:193], v[62:65]
	v_mfma_f32_16x16x32_bf16 v[58:61], v[162:165], v[190:193], v[58:61]
	v_mfma_f32_16x16x32_bf16 v[46:49], v[146:149], v[198:201], v[46:49]
	v_mfma_f32_16x16x32_bf16 v[42:45], v[162:165], v[198:201], v[42:45]
	v_mfma_f32_16x16x32_bf16 v[30:33], v[146:149], v[206:209], v[30:33]
	v_mfma_f32_16x16x32_bf16 v[26:29], v[162:165], v[206:209], v[26:29]
	v_mfma_f32_16x16x32_bf16 v[14:17], v[146:149], v[214:217], v[14:17]
	v_mfma_f32_16x16x32_bf16 v[10:13], v[162:165], v[214:217], v[10:13]
	v_mfma_f32_16x16x32_bf16 v[62:65], v[158:161], v[194:197], v[62:65]
	v_mfma_f32_16x16x32_bf16 v[58:61], v[166:169], v[194:197], v[58:61]
	v_mfma_f32_16x16x32_bf16 v[46:49], v[158:161], v[202:205], v[46:49]
	v_mfma_f32_16x16x32_bf16 v[42:45], v[166:169], v[202:205], v[42:45]
	v_mfma_f32_16x16x32_bf16 v[30:33], v[158:161], v[210:213], v[30:33]
	v_mfma_f32_16x16x32_bf16 v[26:29], v[166:169], v[210:213], v[26:29]
	v_mfma_f32_16x16x32_bf16 v[14:17], v[158:161], v[218:221], v[14:17]
	v_mfma_f32_16x16x32_bf16 v[10:13], v[166:169], v[218:221], v[10:13]
	s_setprio 0
	s_setprio 1
	v_mfma_f32_16x16x32_bf16 v[54:57], v[170:173], v[190:193], v[54:57]
	v_mfma_f32_16x16x32_bf16 v[50:53], v[182:185], v[190:193], v[50:53]
	v_mfma_f32_16x16x32_bf16 v[38:41], v[170:173], v[198:201], v[38:41]
	v_mfma_f32_16x16x32_bf16 v[34:37], v[182:185], v[198:201], v[34:37]
	v_mfma_f32_16x16x32_bf16 v[22:25], v[170:173], v[206:209], v[22:25]
	v_mfma_f32_16x16x32_bf16 v[18:21], v[182:185], v[206:209], v[18:21]
	v_mfma_f32_16x16x32_bf16 v[6:9], v[170:173], v[214:217], v[6:9]
	v_mfma_f32_16x16x32_bf16 v[2:5], v[182:185], v[214:217], v[2:5]
	v_mfma_f32_16x16x32_bf16 v[54:57], v[178:181], v[194:197], v[54:57]
	v_mfma_f32_16x16x32_bf16 v[50:53], v[186:189], v[194:197], v[50:53]
	v_mfma_f32_16x16x32_bf16 v[38:41], v[178:181], v[202:205], v[38:41]
	v_mfma_f32_16x16x32_bf16 v[34:37], v[186:189], v[202:205], v[34:37]
	v_mfma_f32_16x16x32_bf16 v[22:25], v[178:181], v[210:213], v[22:25]
	v_mfma_f32_16x16x32_bf16 v[18:21], v[186:189], v[210:213], v[18:21]
	v_mfma_f32_16x16x32_bf16 v[6:9], v[178:181], v[218:221], v[6:9]
	v_mfma_f32_16x16x32_bf16 v[2:5], v[186:189], v[218:221], v[2:5]
	s_setprio 0
	s_barrier
	s_add_i32 s59, s59, 2
	s_add_u32 s57, s57, 0x100
	s_addc_u32 s58, s58, 0
	s_cmp_gt_u32 s59, 13
	s_mov_b64 s[36:37], s[38:39]
	s_cbranch_scc0 .LBB0_1224
	s_branch .Lpeel_exit_1224
	.p2alignl 6, 3212836864

.LBB0_1322:
	s_ashr_i32 s23, s22, 31
	s_lshl_b64 s[24:25], s[22:23], 19
	s_add_u32 s24, s3, s24
	s_addc_u32 s25, s14, s25
	s_and_b64 s[26:27], s[0:1], exec
	s_cselect_b32 s23, s25, s29
	s_cselect_b32 s50, s24, s28
	s_ashr_i32 s21, s20, 31
	s_lshl_b64 s[26:27], s[20:21], 19
	s_add_u32 s26, s15, s26
	s_addc_u32 s27, s16, s27
	s_and_b64 s[34:35], s[0:1], exec
	s_cselect_b32 s21, s27, s31
	s_cselect_b32 s51, s26, s30
	s_add_u32 s52, s30, 0x100
	s_addc_u32 s53, s31, 0
	s_mov_b32 s54, -2
	ds_read_b128 v[148:151], v154
	ds_read_b128 v[160:163], v154 offset:1024
	ds_read_b128 v[164:167], v154 offset:2048
	ds_read_b128 v[168:171], v154 offset:3072
	ds_read_b128 v[178:181], v155
	ds_read_b128 v[182:185], v155 offset:1024
	ds_read_b128 v[186:189], v155 offset:2048
	ds_read_b128 v[190:193], v155 offset:3072
	s_add_u32 s30, s28, 0x100
	s_addc_u32 s31, s29, 0
	s_cmp_eq_u32 s54, 12
	s_cselect_b32 s37, s23, s31
	s_cselect_b32 s36, s50, s30
	s_cselect_b32 s35, s21, s53
	s_cselect_b32 s34, s51, s52
	v_lshl_add_u64 v[172:173], s[28:29], 0, v[140:141]
	s_add_i32 m0, s39, 0xc000
	ds_read_b128 v[194:197], v156
	ds_read_b128 v[198:201], v156 offset:1024
	ds_read_b128 v[202:205], v156 offset:2048
	ds_read_b128 v[206:209], v156 offset:3072
	ds_read_b128 v[210:213], v156 offset:4096
	ds_read_b128 v[214:217], v156 offset:5120
	ds_read_b128 v[218:221], v156 offset:6144
	ds_read_b128 v[222:225], v156 offset:7168
	global_load_lds_dwordx4 v[172:173], off
	v_lshl_add_u64 v[172:173], s[28:29], 0, v[142:143]
	s_add_i32 m0, s39, 0xe000
	s_nop 0
	global_load_lds_dwordx4 v[172:173], off
	s_waitcnt vmcnt(8)
	s_waitcnt lgkmcnt(0)
	s_barrier
	s_setprio 1
	s_waitcnt lgkmcnt(0)
	v_mfma_f32_16x16x32_bf16 v[126:129], v[148:151], v[194:197], 0
	v_mfma_f32_16x16x32_bf16 v[122:125], v[164:167], v[194:197], 0
	v_mfma_f32_16x16x32_bf16 v[110:113], v[148:151], v[202:205], 0
	v_mfma_f32_16x16x32_bf16 v[106:109], v[164:167], v[202:205], 0
	v_mfma_f32_16x16x32_bf16 v[94:97], v[148:151], v[210:213], 0
	v_mfma_f32_16x16x32_bf16 v[90:93], v[164:167], v[210:213], 0
	v_mfma_f32_16x16x32_bf16 v[78:81], v[148:151], v[218:221], 0
	v_mfma_f32_16x16x32_bf16 v[74:77], v[164:167], v[218:221], 0
	v_mfma_f32_16x16x32_bf16 v[126:129], v[160:163], v[198:201], v[126:129]
	v_mfma_f32_16x16x32_bf16 v[122:125], v[168:171], v[198:201], v[122:125]
	v_mfma_f32_16x16x32_bf16 v[110:113], v[160:163], v[206:209], v[110:113]
	v_mfma_f32_16x16x32_bf16 v[106:109], v[168:171], v[206:209], v[106:109]
	v_mfma_f32_16x16x32_bf16 v[94:97], v[160:163], v[214:217], v[94:97]
	v_mfma_f32_16x16x32_bf16 v[90:93], v[168:171], v[214:217], v[90:93]
	v_mfma_f32_16x16x32_bf16 v[78:81], v[160:163], v[222:225], v[78:81]
	v_mfma_f32_16x16x32_bf16 v[74:77], v[168:171], v[222:225], v[74:77]
	s_setprio 0
	s_setprio 1
	v_mfma_f32_16x16x32_bf16 v[118:121], v[178:181], v[194:197], 0
	v_mfma_f32_16x16x32_bf16 v[114:117], v[186:189], v[194:197], 0
	v_mfma_f32_16x16x32_bf16 v[102:105], v[178:181], v[202:205], 0
	v_mfma_f32_16x16x32_bf16 v[98:101], v[186:189], v[202:205], 0
	v_mfma_f32_16x16x32_bf16 v[86:89], v[178:181], v[210:213], 0
	v_mfma_f32_16x16x32_bf16 v[82:85], v[186:189], v[210:213], 0
	v_mfma_f32_16x16x32_bf16 v[70:73], v[178:181], v[218:221], 0
	v_mfma_f32_16x16x32_bf16 v[66:69], v[186:189], v[218:221], 0
	v_mfma_f32_16x16x32_bf16 v[118:121], v[182:185], v[198:201], v[118:121]
	v_mfma_f32_16x16x32_bf16 v[114:117], v[190:193], v[198:201], v[114:117]
	v_mfma_f32_16x16x32_bf16 v[102:105], v[182:185], v[206:209], v[102:105]
	v_mfma_f32_16x16x32_bf16 v[98:101], v[190:193], v[206:209], v[98:101]
	v_mfma_f32_16x16x32_bf16 v[86:89], v[182:185], v[214:217], v[86:89]
	v_mfma_f32_16x16x32_bf16 v[82:85], v[190:193], v[214:217], v[82:85]
	v_mfma_f32_16x16x32_bf16 v[70:73], v[182:185], v[222:225], v[70:73]
	v_mfma_f32_16x16x32_bf16 v[66:69], v[190:193], v[222:225], v[66:69]
	s_setprio 0
	s_barrier
	s_add_i32 s28, s47, s38
	v_lshl_add_u64 v[172:173], s[34:35], 0, v[132:133]
	s_mov_b32 m0, s28
	ds_read_b128 v[194:197], v156 offset:16384
	ds_read_b128 v[198:201], v156 offset:17408
	ds_read_b128 v[202:205], v156 offset:18432
	ds_read_b128 v[206:209], v156 offset:19456
	ds_read_b128 v[210:213], v156 offset:20480
	ds_read_b128 v[214:217], v156 offset:21504
	ds_read_b128 v[218:221], v156 offset:22528
	ds_read_b128 v[222:225], v156 offset:23552
	global_load_lds_dwordx4 v[172:173], off
	s_add_i32 m0, s28, 0x2000
	s_add_u32 s28, s34, 0x40000
	v_lshl_add_u64 v[226:227], s[34:35], 0, v[136:137]
	s_addc_u32 s29, s35, 0
	s_add_i32 s55, s48, s38
	global_load_lds_dwordx4 v[226:227], off
	v_lshl_add_u64 v[228:229], s[28:29], 0, v[132:133]
	s_mov_b32 m0, s55
	v_lshl_add_u64 v[230:231], s[36:37], 0, v[134:135]
	global_load_lds_dwordx4 v[228:229], off
	v_lshl_add_u64 v[228:229], s[28:29], 0, v[136:137]
	s_add_i32 m0, s55, 0x2000
	s_nop 0
	global_load_lds_dwordx4 v[228:229], off
	v_lshl_add_u64 v[228:229], s[36:37], 0, v[130:131]
	s_mov_b32 m0, s39
	s_nop 0
	global_load_lds_dwordx4 v[228:229], off
	s_mov_b32 m0, s40
	s_nop 0
	global_load_lds_dwordx4 v[230:231], off
	s_waitcnt vmcnt(8)
	s_waitcnt lgkmcnt(0)
	s_barrier
	s_setprio 1
	s_waitcnt lgkmcnt(0)
	v_mfma_f32_16x16x32_bf16 v[62:65], v[148:151], v[194:197], 0
	v_mfma_f32_16x16x32_bf16 v[58:61], v[164:167], v[194:197], 0
	v_mfma_f32_16x16x32_bf16 v[46:49], v[148:151], v[202:205], 0
	v_mfma_f32_16x16x32_bf16 v[42:45], v[164:167], v[202:205], 0
	v_mfma_f32_16x16x32_bf16 v[30:33], v[148:151], v[210:213], 0
	v_mfma_f32_16x16x32_bf16 v[26:29], v[164:167], v[210:213], 0
	v_mfma_f32_16x16x32_bf16 v[14:17], v[148:151], v[218:221], 0
	v_mfma_f32_16x16x32_bf16 v[10:13], v[164:167], v[218:221], 0
	v_mfma_f32_16x16x32_bf16 v[62:65], v[160:163], v[198:201], v[62:65]
	v_mfma_f32_16x16x32_bf16 v[58:61], v[168:171], v[198:201], v[58:61]
	v_mfma_f32_16x16x32_bf16 v[46:49], v[160:163], v[206:209], v[46:49]
	v_mfma_f32_16x16x32_bf16 v[42:45], v[168:171], v[206:209], v[42:45]
	v_mfma_f32_16x16x32_bf16 v[30:33], v[160:163], v[214:217], v[30:33]
	v_mfma_f32_16x16x32_bf16 v[26:29], v[168:171], v[214:217], v[26:29]
	v_mfma_f32_16x16x32_bf16 v[14:17], v[160:163], v[222:225], v[14:17]
	v_mfma_f32_16x16x32_bf16 v[10:13], v[168:171], v[222:225], v[10:13]
	s_setprio 0
	s_setprio 1
	v_mfma_f32_16x16x32_bf16 v[54:57], v[178:181], v[194:197], 0
	v_mfma_f32_16x16x32_bf16 v[50:53], v[186:189], v[194:197], 0
	v_mfma_f32_16x16x32_bf16 v[38:41], v[178:181], v[202:205], 0
	v_mfma_f32_16x16x32_bf16 v[34:37], v[186:189], v[202:205], 0
	v_mfma_f32_16x16x32_bf16 v[22:25], v[178:181], v[210:213], 0
	v_mfma_f32_16x16x32_bf16 v[18:21], v[186:189], v[210:213], 0
	v_mfma_f32_16x16x32_bf16 v[6:9], v[178:181], v[218:221], 0
	v_mfma_f32_16x16x32_bf16 v[2:5], v[186:189], v[218:221], 0
	v_mfma_f32_16x16x32_bf16 v[54:57], v[182:185], v[198:201], v[54:57]
	v_mfma_f32_16x16x32_bf16 v[50:53], v[190:193], v[198:201], v[50:53]
	v_mfma_f32_16x16x32_bf16 v[38:41], v[182:185], v[206:209], v[38:41]
	v_mfma_f32_16x16x32_bf16 v[34:37], v[190:193], v[206:209], v[34:37]
	v_mfma_f32_16x16x32_bf16 v[22:25], v[182:185], v[214:217], v[22:25]
	v_mfma_f32_16x16x32_bf16 v[18:21], v[190:193], v[214:217], v[18:21]
	v_mfma_f32_16x16x32_bf16 v[6:9], v[182:185], v[222:225], v[6:9]
	v_mfma_f32_16x16x32_bf16 v[2:5], v[190:193], v[222:225], v[2:5]
	s_setprio 0
	s_barrier
	s_add_i32 s55, 0, 0x18000
	v_add_u32_e32 v138, s55, v152
	s_add_i32 s56, 0, 0x1c000
	ds_read_b128 v[148:151], v138
	ds_read_b128 v[160:163], v138 offset:1024
	ds_read_b128 v[164:167], v138 offset:2048
	ds_read_b128 v[168:171], v138 offset:3072
	v_add_u32_e32 v138, s56, v152
	ds_read_b128 v[178:181], v138
	ds_read_b128 v[182:185], v138 offset:1024
	ds_read_b128 v[186:189], v138 offset:2048
	ds_read_b128 v[190:193], v138 offset:3072
	s_add_u32 s28, s36, 0x40000
	s_addc_u32 s29, s37, 0
	s_mov_b32 m0, s41
	v_lshl_add_u64 v[232:233], s[28:29], 0, v[130:131]
	ds_read_b128 v[194:197], v156 offset:32768
	ds_read_b128 v[198:201], v156 offset:33792
	ds_read_b128 v[202:205], v156 offset:34816
	ds_read_b128 v[206:209], v156 offset:35840
	ds_read_b128 v[210:213], v156 offset:36864
	ds_read_b128 v[214:217], v156 offset:37888
	ds_read_b128 v[218:221], v156 offset:38912
	ds_read_b128 v[222:225], v156 offset:39936
	global_load_lds_dwordx4 v[232:233], off
	v_lshl_add_u64 v[232:233], s[28:29], 0, v[134:135]
	s_mov_b32 m0, s42
	s_nop 0
	global_load_lds_dwordx4 v[232:233], off
	s_waitcnt vmcnt(8)
	s_waitcnt lgkmcnt(0)
	s_barrier
	s_setprio 1
	s_waitcnt lgkmcnt(0)
	v_mfma_f32_16x16x32_bf16 v[126:129], v[148:151], v[194:197], v[126:129]
	v_mfma_f32_16x16x32_bf16 v[122:125], v[164:167], v[194:197], v[122:125]
	v_mfma_f32_16x16x32_bf16 v[110:113], v[148:151], v[202:205], v[110:113]
	v_mfma_f32_16x16x32_bf16 v[106:109], v[164:167], v[202:205], v[106:109]
	v_mfma_f32_16x16x32_bf16 v[94:97], v[148:151], v[210:213], v[94:97]
	v_mfma_f32_16x16x32_bf16 v[90:93], v[164:167], v[210:213], v[90:93]
	v_mfma_f32_16x16x32_bf16 v[78:81], v[148:151], v[218:221], v[78:81]
	v_mfma_f32_16x16x32_bf16 v[74:77], v[164:167], v[218:221], v[74:77]
	v_mfma_f32_16x16x32_bf16 v[126:129], v[160:163], v[198:201], v[126:129]
	v_mfma_f32_16x16x32_bf16 v[122:125], v[168:171], v[198:201], v[122:125]
	v_mfma_f32_16x16x32_bf16 v[110:113], v[160:163], v[206:209], v[110:113]
	v_mfma_f32_16x16x32_bf16 v[106:109], v[168:171], v[206:209], v[106:109]
	v_mfma_f32_16x16x32_bf16 v[94:97], v[160:163], v[214:217], v[94:97]
	v_mfma_f32_16x16x32_bf16 v[90:93], v[168:171], v[214:217], v[90:93]
	v_mfma_f32_16x16x32_bf16 v[78:81], v[160:163], v[222:225], v[78:81]
	v_mfma_f32_16x16x32_bf16 v[74:77], v[168:171], v[222:225], v[74:77]
	s_setprio 0
	s_setprio 1
	v_mfma_f32_16x16x32_bf16 v[118:121], v[178:181], v[194:197], v[118:121]
	v_mfma_f32_16x16x32_bf16 v[114:117], v[186:189], v[194:197], v[114:117]
	v_mfma_f32_16x16x32_bf16 v[102:105], v[178:181], v[202:205], v[102:105]
	v_mfma_f32_16x16x32_bf16 v[98:101], v[186:189], v[202:205], v[98:101]
	v_mfma_f32_16x16x32_bf16 v[86:89], v[178:181], v[210:213], v[86:89]
	v_mfma_f32_16x16x32_bf16 v[82:85], v[186:189], v[210:213], v[82:85]
	v_mfma_f32_16x16x32_bf16 v[70:73], v[178:181], v[218:221], v[70:73]
	v_mfma_f32_16x16x32_bf16 v[66:69], v[186:189], v[218:221], v[66:69]
	v_mfma_f32_16x16x32_bf16 v[118:121], v[182:185], v[198:201], v[118:121]
	v_mfma_f32_16x16x32_bf16 v[114:117], v[190:193], v[198:201], v[114:117]
	v_mfma_f32_16x16x32_bf16 v[102:105], v[182:185], v[206:209], v[102:105]
	v_mfma_f32_16x16x32_bf16 v[98:101], v[190:193], v[206:209], v[98:101]
	v_mfma_f32_16x16x32_bf16 v[86:89], v[182:185], v[214:217], v[86:89]
	v_mfma_f32_16x16x32_bf16 v[82:85], v[190:193], v[214:217], v[82:85]
	v_mfma_f32_16x16x32_bf16 v[70:73], v[182:185], v[222:225], v[70:73]
	v_mfma_f32_16x16x32_bf16 v[66:69], v[190:193], v[222:225], v[66:69]
	s_setprio 0
	s_barrier
	s_add_i32 s28, s55, s38
	v_lshl_add_u64 v[172:173], v[172:173], 0, s[12:13]
	s_mov_b32 m0, s28
	ds_read_b128 v[194:197], v156 offset:49152
	ds_read_b128 v[198:201], v156 offset:50176
	ds_read_b128 v[202:205], v156 offset:51200
	ds_read_b128 v[206:209], v156 offset:52224
	ds_read_b128 v[210:213], v156 offset:53248
	ds_read_b128 v[214:217], v156 offset:54272
	ds_read_b128 v[218:221], v156 offset:55296
	ds_read_b128 v[222:225], v156 offset:56320
	global_load_lds_dwordx4 v[172:173], off
	s_add_i32 m0, s28, 0x2000
	s_add_u32 s28, s34, 0x40080
	v_lshl_add_u64 v[172:173], v[226:227], 0, s[12:13]
	s_addc_u32 s29, s35, 0
	s_add_i32 s34, s56, s38
	global_load_lds_dwordx4 v[172:173], off
	v_lshl_add_u64 v[172:173], s[28:29], 0, v[132:133]
	s_mov_b32 m0, s34
	s_nop 0
	global_load_lds_dwordx4 v[172:173], off
	v_lshl_add_u64 v[172:173], s[28:29], 0, v[136:137]
	s_add_i32 m0, s34, 0x2000
	s_nop 0
	global_load_lds_dwordx4 v[172:173], off
	v_lshl_add_u64 v[172:173], v[228:229], 0, s[12:13]
	s_mov_b32 m0, s44
	s_nop 0
	global_load_lds_dwordx4 v[172:173], off
	v_lshl_add_u64 v[172:173], v[230:231], 0, s[12:13]
	s_mov_b32 m0, s45
	s_nop 0
	global_load_lds_dwordx4 v[172:173], off
	s_waitcnt vmcnt(8)
	s_waitcnt lgkmcnt(0)
	s_barrier
	s_setprio 1
	s_waitcnt lgkmcnt(0)
	v_mfma_f32_16x16x32_bf16 v[62:65], v[148:151], v[194:197], v[62:65]
	v_mfma_f32_16x16x32_bf16 v[58:61], v[164:167], v[194:197], v[58:61]
	v_mfma_f32_16x16x32_bf16 v[46:49], v[148:151], v[202:205], v[46:49]
	v_mfma_f32_16x16x32_bf16 v[42:45], v[164:167], v[202:205], v[42:45]
	v_mfma_f32_16x16x32_bf16 v[30:33], v[148:151], v[210:213], v[30:33]
	v_mfma_f32_16x16x32_bf16 v[26:29], v[164:167], v[210:213], v[26:29]
	v_mfma_f32_16x16x32_bf16 v[14:17], v[148:151], v[218:221], v[14:17]
	v_mfma_f32_16x16x32_bf16 v[10:13], v[164:167], v[218:221], v[10:13]
	v_mfma_f32_16x16x32_bf16 v[62:65], v[160:163], v[198:201], v[62:65]
	v_mfma_f32_16x16x32_bf16 v[58:61], v[168:171], v[198:201], v[58:61]
	v_mfma_f32_16x16x32_bf16 v[46:49], v[160:163], v[206:209], v[46:49]
	v_mfma_f32_16x16x32_bf16 v[42:45], v[168:171], v[206:209], v[42:45]
	v_mfma_f32_16x16x32_bf16 v[30:33], v[160:163], v[214:217], v[30:33]
	v_mfma_f32_16x16x32_bf16 v[26:29], v[168:171], v[214:217], v[26:29]
	v_mfma_f32_16x16x32_bf16 v[14:17], v[160:163], v[222:225], v[14:17]
	v_mfma_f32_16x16x32_bf16 v[10:13], v[168:171], v[222:225], v[10:13]
	s_setprio 0
	s_setprio 1
	v_mfma_f32_16x16x32_bf16 v[54:57], v[178:181], v[194:197], v[54:57]
	v_mfma_f32_16x16x32_bf16 v[50:53], v[186:189], v[194:197], v[50:53]
	v_mfma_f32_16x16x32_bf16 v[38:41], v[178:181], v[202:205], v[38:41]
	v_mfma_f32_16x16x32_bf16 v[34:37], v[186:189], v[202:205], v[34:37]
	v_mfma_f32_16x16x32_bf16 v[22:25], v[178:181], v[210:213], v[22:25]
	v_mfma_f32_16x16x32_bf16 v[18:21], v[186:189], v[210:213], v[18:21]
	v_mfma_f32_16x16x32_bf16 v[6:9], v[178:181], v[218:221], v[6:9]
	v_mfma_f32_16x16x32_bf16 v[2:5], v[186:189], v[218:221], v[2:5]
	v_mfma_f32_16x16x32_bf16 v[54:57], v[182:185], v[198:201], v[54:57]
	v_mfma_f32_16x16x32_bf16 v[50:53], v[190:193], v[198:201], v[50:53]
	v_mfma_f32_16x16x32_bf16 v[38:41], v[182:185], v[206:209], v[38:41]
	v_mfma_f32_16x16x32_bf16 v[34:37], v[190:193], v[206:209], v[34:37]
	v_mfma_f32_16x16x32_bf16 v[22:25], v[182:185], v[214:217], v[22:25]
	v_mfma_f32_16x16x32_bf16 v[18:21], v[190:193], v[214:217], v[18:21]
	v_mfma_f32_16x16x32_bf16 v[6:9], v[182:185], v[222:225], v[6:9]
	v_mfma_f32_16x16x32_bf16 v[2:5], v[190:193], v[222:225], v[2:5]
	s_setprio 0
	s_barrier
	s_add_i32 s54, s54, 2
	s_add_u32 s52, s52, 0x100
	s_addc_u32 s53, s53, 0
	s_cmp_gt_u32 s54, 13
	s_mov_b64 s[28:29], s[30:31]
	s_cbranch_scc0 .LBB0_1323
	s_branch .Lpeel_exit_1323
	.p2alignl 6, 3212836864

.LBB0_1495:
	s_ashr_i32 s25, s24, 31
	s_lshl_b64 s[26:27], s[24:25], 19
	s_add_u32 s26, s3, s26
	s_addc_u32 s27, s14, s27
	s_and_b64 s[28:29], s[4:5], exec
	s_cselect_b32 s25, s27, s35
	s_cselect_b32 s31, s26, s34
	s_ashr_i32 s23, s22, 31
	s_lshl_b64 s[28:29], s[22:23], 19
	s_add_u32 s28, s15, s28
	s_addc_u32 s29, s16, s29
	s_and_b64 s[38:39], s[4:5], exec
	s_cselect_b32 s23, s29, s37
	s_cselect_b32 s54, s28, s36
	s_add_u32 s55, s36, 0x100
	s_addc_u32 s56, s37, 0
	s_mov_b32 s57, -2
	s_waitcnt lgkmcnt(0)
	ds_read_b128 v[146:149], v153
	ds_read_b128 v[158:161], v153 offset:1024
	ds_read_b128 v[162:165], v153 offset:2048
	ds_read_b128 v[166:169], v153 offset:3072
	ds_read_b128 v[170:173], v154
	ds_read_b128 v[178:181], v154 offset:1024
	ds_read_b128 v[182:185], v154 offset:2048
	ds_read_b128 v[186:189], v154 offset:3072
	s_add_u32 s36, s34, 0x100
	s_addc_u32 s37, s35, 0
	s_cmp_eq_u32 s57, 12
	s_cselect_b32 s41, s25, s37
	s_cselect_b32 s40, s31, s36
	s_cselect_b32 s39, s23, s56
	s_cselect_b32 s38, s54, s55
	v_lshl_add_u64 v[222:223], s[34:35], 0, v[138:139]
	s_add_i32 m0, s42, 0xc000
	ds_read_b128 v[190:193], v155
	ds_read_b128 v[194:197], v155 offset:1024
	ds_read_b128 v[198:201], v155 offset:2048
	ds_read_b128 v[202:205], v155 offset:3072
	ds_read_b128 v[206:209], v155 offset:4096
	ds_read_b128 v[210:213], v155 offset:5120
	ds_read_b128 v[214:217], v155 offset:6144
	ds_read_b128 v[218:221], v155 offset:7168
	global_load_lds_dwordx4 v[222:223], off
	v_lshl_add_u64 v[222:223], s[34:35], 0, v[140:141]
	s_add_i32 m0, s42, 0xe000
	s_nop 0
	global_load_lds_dwordx4 v[222:223], off
	s_waitcnt vmcnt(8)
	s_waitcnt lgkmcnt(0)
	s_barrier
	s_setprio 1
	s_waitcnt lgkmcnt(0)
	v_mfma_f32_16x16x32_bf16 v[126:129], v[146:149], v[190:193], 0
	v_mfma_f32_16x16x32_bf16 v[122:125], v[162:165], v[190:193], 0
	v_mfma_f32_16x16x32_bf16 v[110:113], v[146:149], v[198:201], 0
	v_mfma_f32_16x16x32_bf16 v[106:109], v[162:165], v[198:201], 0
	v_mfma_f32_16x16x32_bf16 v[94:97], v[146:149], v[206:209], 0
	v_mfma_f32_16x16x32_bf16 v[90:93], v[162:165], v[206:209], 0
	v_mfma_f32_16x16x32_bf16 v[78:81], v[146:149], v[214:217], 0
	v_mfma_f32_16x16x32_bf16 v[74:77], v[162:165], v[214:217], 0
	v_mfma_f32_16x16x32_bf16 v[126:129], v[158:161], v[194:197], v[126:129]
	v_mfma_f32_16x16x32_bf16 v[122:125], v[166:169], v[194:197], v[122:125]
	v_mfma_f32_16x16x32_bf16 v[110:113], v[158:161], v[202:205], v[110:113]
	v_mfma_f32_16x16x32_bf16 v[106:109], v[166:169], v[202:205], v[106:109]
	v_mfma_f32_16x16x32_bf16 v[94:97], v[158:161], v[210:213], v[94:97]
	v_mfma_f32_16x16x32_bf16 v[90:93], v[166:169], v[210:213], v[90:93]
	v_mfma_f32_16x16x32_bf16 v[78:81], v[158:161], v[218:221], v[78:81]
	v_mfma_f32_16x16x32_bf16 v[74:77], v[166:169], v[218:221], v[74:77]
	s_setprio 0
	s_setprio 1
	v_mfma_f32_16x16x32_bf16 v[118:121], v[170:173], v[190:193], 0
	v_mfma_f32_16x16x32_bf16 v[114:117], v[182:185], v[190:193], 0
	v_mfma_f32_16x16x32_bf16 v[102:105], v[170:173], v[198:201], 0
	v_mfma_f32_16x16x32_bf16 v[98:101], v[182:185], v[198:201], 0
	v_mfma_f32_16x16x32_bf16 v[86:89], v[170:173], v[206:209], 0
	v_mfma_f32_16x16x32_bf16 v[82:85], v[182:185], v[206:209], 0
	v_mfma_f32_16x16x32_bf16 v[70:73], v[170:173], v[214:217], 0
	v_mfma_f32_16x16x32_bf16 v[66:69], v[182:185], v[214:217], 0
	v_mfma_f32_16x16x32_bf16 v[118:121], v[178:181], v[194:197], v[118:121]
	v_mfma_f32_16x16x32_bf16 v[114:117], v[186:189], v[194:197], v[114:117]
	v_mfma_f32_16x16x32_bf16 v[102:105], v[178:181], v[202:205], v[102:105]
	v_mfma_f32_16x16x32_bf16 v[98:101], v[186:189], v[202:205], v[98:101]
	v_mfma_f32_16x16x32_bf16 v[86:89], v[178:181], v[210:213], v[86:89]
	v_mfma_f32_16x16x32_bf16 v[82:85], v[186:189], v[210:213], v[82:85]
	v_mfma_f32_16x16x32_bf16 v[70:73], v[178:181], v[218:221], v[70:73]
	v_mfma_f32_16x16x32_bf16 v[66:69], v[186:189], v[218:221], v[66:69]
	s_setprio 0
	s_barrier
	s_add_i32 s34, s51, s17
	v_lshl_add_u64 v[222:223], s[38:39], 0, v[132:133]
	s_mov_b32 m0, s34
	ds_read_b128 v[190:193], v155 offset:16384
	ds_read_b128 v[194:197], v155 offset:17408
	ds_read_b128 v[198:201], v155 offset:18432
	ds_read_b128 v[202:205], v155 offset:19456
	ds_read_b128 v[206:209], v155 offset:20480
	ds_read_b128 v[210:213], v155 offset:21504
	ds_read_b128 v[214:217], v155 offset:22528
	ds_read_b128 v[218:221], v155 offset:23552
	global_load_lds_dwordx4 v[222:223], off
	s_add_i32 m0, s34, 0x2000
	s_add_u32 s34, s38, 0x40000
	v_lshl_add_u64 v[224:225], s[38:39], 0, v[136:137]
	s_addc_u32 s35, s39, 0
	s_add_i32 s58, s52, s17
	global_load_lds_dwordx4 v[224:225], off
	v_lshl_add_u64 v[226:227], s[34:35], 0, v[132:133]
	s_mov_b32 m0, s58
	v_lshl_add_u64 v[228:229], s[40:41], 0, v[134:135]
	global_load_lds_dwordx4 v[226:227], off
	v_lshl_add_u64 v[226:227], s[34:35], 0, v[136:137]
	s_add_i32 m0, s58, 0x2000
	s_nop 0
	global_load_lds_dwordx4 v[226:227], off
	v_lshl_add_u64 v[226:227], s[40:41], 0, v[130:131]
	s_mov_b32 m0, s42
	s_nop 0
	global_load_lds_dwordx4 v[226:227], off
	s_mov_b32 m0, s43
	s_nop 0
	global_load_lds_dwordx4 v[228:229], off
	s_waitcnt vmcnt(8)
	s_waitcnt lgkmcnt(0)
	s_barrier
	s_setprio 1
	s_waitcnt lgkmcnt(0)
	v_mfma_f32_16x16x32_bf16 v[62:65], v[146:149], v[190:193], 0
	v_mfma_f32_16x16x32_bf16 v[58:61], v[162:165], v[190:193], 0
	v_mfma_f32_16x16x32_bf16 v[46:49], v[146:149], v[198:201], 0
	v_mfma_f32_16x16x32_bf16 v[42:45], v[162:165], v[198:201], 0
	v_mfma_f32_16x16x32_bf16 v[30:33], v[146:149], v[206:209], 0
	v_mfma_f32_16x16x32_bf16 v[26:29], v[162:165], v[206:209], 0
	v_mfma_f32_16x16x32_bf16 v[14:17], v[146:149], v[214:217], 0
	v_mfma_f32_16x16x32_bf16 v[10:13], v[162:165], v[214:217], 0
	v_mfma_f32_16x16x32_bf16 v[62:65], v[158:161], v[194:197], v[62:65]
	v_mfma_f32_16x16x32_bf16 v[58:61], v[166:169], v[194:197], v[58:61]
	v_mfma_f32_16x16x32_bf16 v[46:49], v[158:161], v[202:205], v[46:49]
	v_mfma_f32_16x16x32_bf16 v[42:45], v[166:169], v[202:205], v[42:45]
	v_mfma_f32_16x16x32_bf16 v[30:33], v[158:161], v[210:213], v[30:33]
	v_mfma_f32_16x16x32_bf16 v[26:29], v[166:169], v[210:213], v[26:29]
	v_mfma_f32_16x16x32_bf16 v[14:17], v[158:161], v[218:221], v[14:17]
	v_mfma_f32_16x16x32_bf16 v[10:13], v[166:169], v[218:221], v[10:13]
	s_setprio 0
	s_setprio 1
	v_mfma_f32_16x16x32_bf16 v[54:57], v[170:173], v[190:193], 0
	v_mfma_f32_16x16x32_bf16 v[50:53], v[182:185], v[190:193], 0
	v_mfma_f32_16x16x32_bf16 v[38:41], v[170:173], v[198:201], 0
	v_mfma_f32_16x16x32_bf16 v[34:37], v[182:185], v[198:201], 0
	v_mfma_f32_16x16x32_bf16 v[22:25], v[170:173], v[206:209], 0
	v_mfma_f32_16x16x32_bf16 v[18:21], v[182:185], v[206:209], 0
	v_mfma_f32_16x16x32_bf16 v[6:9], v[170:173], v[214:217], 0
	v_mfma_f32_16x16x32_bf16 v[2:5], v[182:185], v[214:217], 0
	v_mfma_f32_16x16x32_bf16 v[54:57], v[178:181], v[194:197], v[54:57]
	v_mfma_f32_16x16x32_bf16 v[50:53], v[186:189], v[194:197], v[50:53]
	v_mfma_f32_16x16x32_bf16 v[38:41], v[178:181], v[202:205], v[38:41]
	v_mfma_f32_16x16x32_bf16 v[34:37], v[186:189], v[202:205], v[34:37]
	v_mfma_f32_16x16x32_bf16 v[22:25], v[178:181], v[210:213], v[22:25]
	v_mfma_f32_16x16x32_bf16 v[18:21], v[186:189], v[210:213], v[18:21]
	v_mfma_f32_16x16x32_bf16 v[6:9], v[178:181], v[218:221], v[6:9]
	v_mfma_f32_16x16x32_bf16 v[2:5], v[186:189], v[218:221], v[2:5]
	s_setprio 0
	s_barrier
	s_add_i32 s58, 0, 0x18000
	v_add_u32_e32 v157, s58, v151
	s_add_i32 s59, 0, 0x1c000
	ds_read_b128 v[146:149], v157
	ds_read_b128 v[158:161], v157 offset:1024
	ds_read_b128 v[162:165], v157 offset:2048
	ds_read_b128 v[166:169], v157 offset:3072
	v_add_u32_e32 v157, s59, v151
	ds_read_b128 v[170:173], v157
	ds_read_b128 v[178:181], v157 offset:1024
	ds_read_b128 v[182:185], v157 offset:2048
	ds_read_b128 v[186:189], v157 offset:3072
	s_add_u32 s34, s40, 0x40000
	s_addc_u32 s35, s41, 0
	s_mov_b32 m0, s44
	v_lshl_add_u64 v[230:231], s[34:35], 0, v[130:131]
	ds_read_b128 v[190:193], v155 offset:32768
	ds_read_b128 v[194:197], v155 offset:33792
	ds_read_b128 v[198:201], v155 offset:34816
	ds_read_b128 v[202:205], v155 offset:35840
	ds_read_b128 v[206:209], v155 offset:36864
	ds_read_b128 v[210:213], v155 offset:37888
	ds_read_b128 v[214:217], v155 offset:38912
	ds_read_b128 v[218:221], v155 offset:39936
	global_load_lds_dwordx4 v[230:231], off
	v_lshl_add_u64 v[230:231], s[34:35], 0, v[134:135]
	s_mov_b32 m0, s45
	s_nop 0
	global_load_lds_dwordx4 v[230:231], off
	s_waitcnt vmcnt(8)
	s_waitcnt lgkmcnt(0)
	s_barrier
	s_setprio 1
	s_waitcnt lgkmcnt(0)
	v_mfma_f32_16x16x32_bf16 v[126:129], v[146:149], v[190:193], v[126:129]
	v_mfma_f32_16x16x32_bf16 v[122:125], v[162:165], v[190:193], v[122:125]
	v_mfma_f32_16x16x32_bf16 v[110:113], v[146:149], v[198:201], v[110:113]
	v_mfma_f32_16x16x32_bf16 v[106:109], v[162:165], v[198:201], v[106:109]
	v_mfma_f32_16x16x32_bf16 v[94:97], v[146:149], v[206:209], v[94:97]
	v_mfma_f32_16x16x32_bf16 v[90:93], v[162:165], v[206:209], v[90:93]
	v_mfma_f32_16x16x32_bf16 v[78:81], v[146:149], v[214:217], v[78:81]
	v_mfma_f32_16x16x32_bf16 v[74:77], v[162:165], v[214:217], v[74:77]
	v_mfma_f32_16x16x32_bf16 v[126:129], v[158:161], v[194:197], v[126:129]
	v_mfma_f32_16x16x32_bf16 v[122:125], v[166:169], v[194:197], v[122:125]
	v_mfma_f32_16x16x32_bf16 v[110:113], v[158:161], v[202:205], v[110:113]
	v_mfma_f32_16x16x32_bf16 v[106:109], v[166:169], v[202:205], v[106:109]
	v_mfma_f32_16x16x32_bf16 v[94:97], v[158:161], v[210:213], v[94:97]
	v_mfma_f32_16x16x32_bf16 v[90:93], v[166:169], v[210:213], v[90:93]
	v_mfma_f32_16x16x32_bf16 v[78:81], v[158:161], v[218:221], v[78:81]
	v_mfma_f32_16x16x32_bf16 v[74:77], v[166:169], v[218:221], v[74:77]
	s_setprio 0
	s_setprio 1
	v_mfma_f32_16x16x32_bf16 v[118:121], v[170:173], v[190:193], v[118:121]
	v_mfma_f32_16x16x32_bf16 v[114:117], v[182:185], v[190:193], v[114:117]
	v_mfma_f32_16x16x32_bf16 v[102:105], v[170:173], v[198:201], v[102:105]
	v_mfma_f32_16x16x32_bf16 v[98:101], v[182:185], v[198:201], v[98:101]
	v_mfma_f32_16x16x32_bf16 v[86:89], v[170:173], v[206:209], v[86:89]
	v_mfma_f32_16x16x32_bf16 v[82:85], v[182:185], v[206:209], v[82:85]
	v_mfma_f32_16x16x32_bf16 v[70:73], v[170:173], v[214:217], v[70:73]
	v_mfma_f32_16x16x32_bf16 v[66:69], v[182:185], v[214:217], v[66:69]
	v_mfma_f32_16x16x32_bf16 v[118:121], v[178:181], v[194:197], v[118:121]
	v_mfma_f32_16x16x32_bf16 v[114:117], v[186:189], v[194:197], v[114:117]
	v_mfma_f32_16x16x32_bf16 v[102:105], v[178:181], v[202:205], v[102:105]
	v_mfma_f32_16x16x32_bf16 v[98:101], v[186:189], v[202:205], v[98:101]
	v_mfma_f32_16x16x32_bf16 v[86:89], v[178:181], v[210:213], v[86:89]
	v_mfma_f32_16x16x32_bf16 v[82:85], v[186:189], v[210:213], v[82:85]
	v_mfma_f32_16x16x32_bf16 v[70:73], v[178:181], v[218:221], v[70:73]
	v_mfma_f32_16x16x32_bf16 v[66:69], v[186:189], v[218:221], v[66:69]
	s_setprio 0
	s_barrier
	s_add_i32 s34, s58, s17
	v_lshl_add_u64 v[222:223], v[222:223], 0, s[18:19]
	s_mov_b32 m0, s34
	ds_read_b128 v[190:193], v155 offset:49152
	ds_read_b128 v[194:197], v155 offset:50176
	ds_read_b128 v[198:201], v155 offset:51200
	ds_read_b128 v[202:205], v155 offset:52224
	ds_read_b128 v[206:209], v155 offset:53248
	ds_read_b128 v[210:213], v155 offset:54272
	ds_read_b128 v[214:217], v155 offset:55296
	ds_read_b128 v[218:221], v155 offset:56320
	global_load_lds_dwordx4 v[222:223], off
	s_add_i32 m0, s34, 0x2000
	s_add_u32 s34, s38, 0x40080
	v_lshl_add_u64 v[222:223], v[224:225], 0, s[18:19]
	s_addc_u32 s35, s39, 0
	s_add_i32 s38, s59, s17
	global_load_lds_dwordx4 v[222:223], off
	v_lshl_add_u64 v[222:223], s[34:35], 0, v[132:133]
	s_mov_b32 m0, s38
	s_nop 0
	global_load_lds_dwordx4 v[222:223], off
	v_lshl_add_u64 v[222:223], s[34:35], 0, v[136:137]
	s_add_i32 m0, s38, 0x2000
	s_nop 0
	global_load_lds_dwordx4 v[222:223], off
	v_lshl_add_u64 v[222:223], v[226:227], 0, s[18:19]
	s_mov_b32 m0, s47
	s_nop 0
	global_load_lds_dwordx4 v[222:223], off
	v_lshl_add_u64 v[222:223], v[228:229], 0, s[18:19]
	s_mov_b32 m0, s48
	s_nop 0
	global_load_lds_dwordx4 v[222:223], off
	s_waitcnt vmcnt(8)
	s_waitcnt lgkmcnt(0)
	s_barrier
	s_setprio 1
	s_waitcnt lgkmcnt(0)
	v_mfma_f32_16x16x32_bf16 v[62:65], v[146:149], v[190:193], v[62:65]
	v_mfma_f32_16x16x32_bf16 v[58:61], v[162:165], v[190:193], v[58:61]
	v_mfma_f32_16x16x32_bf16 v[46:49], v[146:149], v[198:201], v[46:49]
	v_mfma_f32_16x16x32_bf16 v[42:45], v[162:165], v[198:201], v[42:45]
	v_mfma_f32_16x16x32_bf16 v[30:33], v[146:149], v[206:209], v[30:33]
	v_mfma_f32_16x16x32_bf16 v[26:29], v[162:165], v[206:209], v[26:29]
	v_mfma_f32_16x16x32_bf16 v[14:17], v[146:149], v[214:217], v[14:17]
	v_mfma_f32_16x16x32_bf16 v[10:13], v[162:165], v[214:217], v[10:13]
	v_mfma_f32_16x16x32_bf16 v[62:65], v[158:161], v[194:197], v[62:65]
	v_mfma_f32_16x16x32_bf16 v[58:61], v[166:169], v[194:197], v[58:61]
	v_mfma_f32_16x16x32_bf16 v[46:49], v[158:161], v[202:205], v[46:49]
	v_mfma_f32_16x16x32_bf16 v[42:45], v[166:169], v[202:205], v[42:45]
	v_mfma_f32_16x16x32_bf16 v[30:33], v[158:161], v[210:213], v[30:33]
	v_mfma_f32_16x16x32_bf16 v[26:29], v[166:169], v[210:213], v[26:29]
	v_mfma_f32_16x16x32_bf16 v[14:17], v[158:161], v[218:221], v[14:17]
	v_mfma_f32_16x16x32_bf16 v[10:13], v[166:169], v[218:221], v[10:13]
	s_setprio 0
	s_setprio 1
	v_mfma_f32_16x16x32_bf16 v[54:57], v[170:173], v[190:193], v[54:57]
	v_mfma_f32_16x16x32_bf16 v[50:53], v[182:185], v[190:193], v[50:53]
	v_mfma_f32_16x16x32_bf16 v[38:41], v[170:173], v[198:201], v[38:41]
	v_mfma_f32_16x16x32_bf16 v[34:37], v[182:185], v[198:201], v[34:37]
	v_mfma_f32_16x16x32_bf16 v[22:25], v[170:173], v[206:209], v[22:25]
	v_mfma_f32_16x16x32_bf16 v[18:21], v[182:185], v[206:209], v[18:21]
	v_mfma_f32_16x16x32_bf16 v[6:9], v[170:173], v[214:217], v[6:9]
	v_mfma_f32_16x16x32_bf16 v[2:5], v[182:185], v[214:217], v[2:5]
	v_mfma_f32_16x16x32_bf16 v[54:57], v[178:181], v[194:197], v[54:57]
	v_mfma_f32_16x16x32_bf16 v[50:53], v[186:189], v[194:197], v[50:53]
	v_mfma_f32_16x16x32_bf16 v[38:41], v[178:181], v[202:205], v[38:41]
	v_mfma_f32_16x16x32_bf16 v[34:37], v[186:189], v[202:205], v[34:37]
	v_mfma_f32_16x16x32_bf16 v[22:25], v[178:181], v[210:213], v[22:25]
	v_mfma_f32_16x16x32_bf16 v[18:21], v[186:189], v[210:213], v[18:21]
	v_mfma_f32_16x16x32_bf16 v[6:9], v[178:181], v[218:221], v[6:9]
	v_mfma_f32_16x16x32_bf16 v[2:5], v[186:189], v[218:221], v[2:5]
	s_setprio 0
	s_barrier
	s_add_i32 s57, s57, 2
	s_add_u32 s55, s55, 0x100
	s_addc_u32 s56, s56, 0
	s_cmp_gt_u32 s57, 13
	s_mov_b64 s[34:35], s[36:37]
	s_cbranch_scc0 .LBB0_1496
	s_branch .Lpeel_exit_1496
	.p2alignl 6, 3212836864

.LBB0_1589:
	s_ashr_i32 s21, s20, 31
	s_lshl_b64 s[22:23], s[20:21], 19
	s_add_u32 s22, s14, s22
	s_addc_u32 s23, s15, s23
	s_and_b64 s[24:25], s[0:1], exec
	s_cselect_b32 s21, s23, s27
	s_cselect_b32 s49, s22, s26
	s_ashr_i32 s19, s18, 31
	s_lshl_b64 s[24:25], s[18:19], 19
	s_add_u32 s24, s16, s24
	s_addc_u32 s25, s17, s25
	s_and_b64 s[30:31], s[0:1], exec
	s_cselect_b32 s19, s25, s29
	s_cselect_b32 s50, s24, s28
	s_add_u32 s51, s28, 0x100
	s_addc_u32 s52, s29, 0
	s_mov_b32 s53, -2
	s_waitcnt vmcnt(0)
	ds_read_b128 v[146:149], v155
	ds_read_b128 v[160:163], v155 offset:1024
	ds_read_b128 v[164:167], v155 offset:2048
	ds_read_b128 v[168:171], v155 offset:3072
	ds_read_b128 v[178:181], v156
	ds_read_b128 v[182:185], v156 offset:1024
	ds_read_b128 v[186:189], v156 offset:2048
	ds_read_b128 v[190:193], v156 offset:3072
	s_add_u32 s28, s26, 0x100
	s_addc_u32 s29, s27, 0
	s_cmp_eq_u32 s53, 12
	s_cselect_b32 s35, s21, s29
	s_cselect_b32 s34, s49, s28
	s_cselect_b32 s31, s19, s52
	s_cselect_b32 s30, s50, s51
	v_lshl_add_u64 v[150:151], s[26:27], 0, v[138:139]
	s_add_i32 m0, s37, 0xc000
	ds_read_b128 v[194:197], v157
	ds_read_b128 v[198:201], v157 offset:1024
	ds_read_b128 v[202:205], v157 offset:2048
	ds_read_b128 v[206:209], v157 offset:3072
	ds_read_b128 v[210:213], v157 offset:4096
	ds_read_b128 v[214:217], v157 offset:5120
	ds_read_b128 v[218:221], v157 offset:6144
	ds_read_b128 v[222:225], v157 offset:7168
	global_load_lds_dwordx4 v[150:151], off
	v_lshl_add_u64 v[150:151], s[26:27], 0, v[140:141]
	s_add_i32 m0, s37, 0xe000
	s_nop 0
	global_load_lds_dwordx4 v[150:151], off
	s_waitcnt vmcnt(8)
	s_waitcnt lgkmcnt(0)
	s_barrier
	s_setprio 1
	s_waitcnt lgkmcnt(0)
	v_mfma_f32_16x16x32_bf16 v[126:129], v[146:149], v[194:197], 0
	v_mfma_f32_16x16x32_bf16 v[122:125], v[164:167], v[194:197], 0
	v_mfma_f32_16x16x32_bf16 v[110:113], v[146:149], v[202:205], 0
	v_mfma_f32_16x16x32_bf16 v[106:109], v[164:167], v[202:205], 0
	v_mfma_f32_16x16x32_bf16 v[94:97], v[146:149], v[210:213], 0
	v_mfma_f32_16x16x32_bf16 v[90:93], v[164:167], v[210:213], 0
	v_mfma_f32_16x16x32_bf16 v[78:81], v[146:149], v[218:221], 0
	v_mfma_f32_16x16x32_bf16 v[74:77], v[164:167], v[218:221], 0
	v_mfma_f32_16x16x32_bf16 v[126:129], v[160:163], v[198:201], v[126:129]
	v_mfma_f32_16x16x32_bf16 v[122:125], v[168:171], v[198:201], v[122:125]
	v_mfma_f32_16x16x32_bf16 v[110:113], v[160:163], v[206:209], v[110:113]
	v_mfma_f32_16x16x32_bf16 v[106:109], v[168:171], v[206:209], v[106:109]
	v_mfma_f32_16x16x32_bf16 v[94:97], v[160:163], v[214:217], v[94:97]
	v_mfma_f32_16x16x32_bf16 v[90:93], v[168:171], v[214:217], v[90:93]
	v_mfma_f32_16x16x32_bf16 v[78:81], v[160:163], v[222:225], v[78:81]
	v_mfma_f32_16x16x32_bf16 v[74:77], v[168:171], v[222:225], v[74:77]
	s_setprio 0
	s_setprio 1
	v_mfma_f32_16x16x32_bf16 v[118:121], v[178:181], v[194:197], 0
	v_mfma_f32_16x16x32_bf16 v[114:117], v[186:189], v[194:197], 0
	v_mfma_f32_16x16x32_bf16 v[102:105], v[178:181], v[202:205], 0
	v_mfma_f32_16x16x32_bf16 v[98:101], v[186:189], v[202:205], 0
	v_mfma_f32_16x16x32_bf16 v[86:89], v[178:181], v[210:213], 0
	v_mfma_f32_16x16x32_bf16 v[82:85], v[186:189], v[210:213], 0
	v_mfma_f32_16x16x32_bf16 v[70:73], v[178:181], v[218:221], 0
	v_mfma_f32_16x16x32_bf16 v[66:69], v[186:189], v[218:221], 0
	v_mfma_f32_16x16x32_bf16 v[118:121], v[182:185], v[198:201], v[118:121]
	v_mfma_f32_16x16x32_bf16 v[114:117], v[190:193], v[198:201], v[114:117]
	v_mfma_f32_16x16x32_bf16 v[102:105], v[182:185], v[206:209], v[102:105]
	v_mfma_f32_16x16x32_bf16 v[98:101], v[190:193], v[206:209], v[98:101]
	v_mfma_f32_16x16x32_bf16 v[86:89], v[182:185], v[214:217], v[86:89]
	v_mfma_f32_16x16x32_bf16 v[82:85], v[190:193], v[214:217], v[82:85]
	v_mfma_f32_16x16x32_bf16 v[70:73], v[182:185], v[222:225], v[70:73]
	v_mfma_f32_16x16x32_bf16 v[66:69], v[190:193], v[222:225], v[66:69]
	s_setprio 0
	s_barrier
	s_add_i32 s26, s45, s36
	v_lshl_add_u64 v[150:151], s[30:31], 0, v[132:133]
	s_mov_b32 m0, s26
	ds_read_b128 v[194:197], v157 offset:16384
	ds_read_b128 v[198:201], v157 offset:17408
	ds_read_b128 v[202:205], v157 offset:18432
	ds_read_b128 v[206:209], v157 offset:19456
	ds_read_b128 v[210:213], v157 offset:20480
	ds_read_b128 v[214:217], v157 offset:21504
	ds_read_b128 v[218:221], v157 offset:22528
	ds_read_b128 v[222:225], v157 offset:23552
	global_load_lds_dwordx4 v[150:151], off
	s_add_i32 m0, s26, 0x2000
	s_add_u32 s26, s30, 0x40000
	v_lshl_add_u64 v[172:173], s[30:31], 0, v[136:137]
	s_addc_u32 s27, s31, 0
	s_add_i32 s54, s46, s36
	global_load_lds_dwordx4 v[172:173], off
	v_lshl_add_u64 v[226:227], s[26:27], 0, v[132:133]
	s_mov_b32 m0, s54
	v_lshl_add_u64 v[228:229], s[34:35], 0, v[134:135]
	global_load_lds_dwordx4 v[226:227], off
	v_lshl_add_u64 v[226:227], s[26:27], 0, v[136:137]
	s_add_i32 m0, s54, 0x2000
	s_nop 0
	global_load_lds_dwordx4 v[226:227], off
	v_lshl_add_u64 v[226:227], s[34:35], 0, v[130:131]
	s_mov_b32 m0, s37
	s_nop 0
	global_load_lds_dwordx4 v[226:227], off
	s_mov_b32 m0, s38
	s_nop 0
	global_load_lds_dwordx4 v[228:229], off
	s_waitcnt vmcnt(8)
	s_waitcnt lgkmcnt(0)
	s_barrier
	s_setprio 1
	s_waitcnt lgkmcnt(0)
	v_mfma_f32_16x16x32_bf16 v[62:65], v[146:149], v[194:197], 0
	v_mfma_f32_16x16x32_bf16 v[58:61], v[164:167], v[194:197], 0
	v_mfma_f32_16x16x32_bf16 v[46:49], v[146:149], v[202:205], 0
	v_mfma_f32_16x16x32_bf16 v[42:45], v[164:167], v[202:205], 0
	v_mfma_f32_16x16x32_bf16 v[30:33], v[146:149], v[210:213], 0
	v_mfma_f32_16x16x32_bf16 v[26:29], v[164:167], v[210:213], 0
	v_mfma_f32_16x16x32_bf16 v[14:17], v[146:149], v[218:221], 0
	v_mfma_f32_16x16x32_bf16 v[10:13], v[164:167], v[218:221], 0
	v_mfma_f32_16x16x32_bf16 v[62:65], v[160:163], v[198:201], v[62:65]
	v_mfma_f32_16x16x32_bf16 v[58:61], v[168:171], v[198:201], v[58:61]
	v_mfma_f32_16x16x32_bf16 v[46:49], v[160:163], v[206:209], v[46:49]
	v_mfma_f32_16x16x32_bf16 v[42:45], v[168:171], v[206:209], v[42:45]
	v_mfma_f32_16x16x32_bf16 v[30:33], v[160:163], v[214:217], v[30:33]
	v_mfma_f32_16x16x32_bf16 v[26:29], v[168:171], v[214:217], v[26:29]
	v_mfma_f32_16x16x32_bf16 v[14:17], v[160:163], v[222:225], v[14:17]
	v_mfma_f32_16x16x32_bf16 v[10:13], v[168:171], v[222:225], v[10:13]
	s_setprio 0
	s_setprio 1
	v_mfma_f32_16x16x32_bf16 v[54:57], v[178:181], v[194:197], 0
	v_mfma_f32_16x16x32_bf16 v[50:53], v[186:189], v[194:197], 0
	v_mfma_f32_16x16x32_bf16 v[38:41], v[178:181], v[202:205], 0
	v_mfma_f32_16x16x32_bf16 v[34:37], v[186:189], v[202:205], 0
	v_mfma_f32_16x16x32_bf16 v[22:25], v[178:181], v[210:213], 0
	v_mfma_f32_16x16x32_bf16 v[18:21], v[186:189], v[210:213], 0
	v_mfma_f32_16x16x32_bf16 v[6:9], v[178:181], v[218:221], 0
	v_mfma_f32_16x16x32_bf16 v[2:5], v[186:189], v[218:221], 0
	v_mfma_f32_16x16x32_bf16 v[54:57], v[182:185], v[198:201], v[54:57]
	v_mfma_f32_16x16x32_bf16 v[50:53], v[190:193], v[198:201], v[50:53]
	v_mfma_f32_16x16x32_bf16 v[38:41], v[182:185], v[206:209], v[38:41]
	v_mfma_f32_16x16x32_bf16 v[34:37], v[190:193], v[206:209], v[34:37]
	v_mfma_f32_16x16x32_bf16 v[22:25], v[182:185], v[214:217], v[22:25]
	v_mfma_f32_16x16x32_bf16 v[18:21], v[190:193], v[214:217], v[18:21]
	v_mfma_f32_16x16x32_bf16 v[6:9], v[182:185], v[222:225], v[6:9]
	v_mfma_f32_16x16x32_bf16 v[2:5], v[190:193], v[222:225], v[2:5]
	s_setprio 0
	s_barrier
	s_add_i32 s54, 0, 0x18000
	s_add_i32 s55, 0, 0x1c000
	v_add_u32_e32 v168, s54, v153
	v_add_u32_e32 v177, s55, v153
	ds_read_b128 v[146:149], v168
	ds_read_b128 v[160:163], v168 offset:1024
	ds_read_b128 v[164:167], v168 offset:2048
	ds_read_b128 v[168:171], v168 offset:3072
	ds_read_b128 v[178:181], v177
	ds_read_b128 v[182:185], v177 offset:1024
	ds_read_b128 v[186:189], v177 offset:2048
	ds_read_b128 v[190:193], v177 offset:3072
	s_add_u32 s26, s34, 0x40000
	s_addc_u32 s27, s35, 0
	s_mov_b32 m0, s39
	v_lshl_add_u64 v[230:231], s[26:27], 0, v[130:131]
	ds_read_b128 v[194:197], v157 offset:32768
	ds_read_b128 v[198:201], v157 offset:33792
	ds_read_b128 v[202:205], v157 offset:34816
	ds_read_b128 v[206:209], v157 offset:35840
	ds_read_b128 v[210:213], v157 offset:36864
	ds_read_b128 v[214:217], v157 offset:37888
	ds_read_b128 v[218:221], v157 offset:38912
	ds_read_b128 v[222:225], v157 offset:39936
	global_load_lds_dwordx4 v[230:231], off
	v_lshl_add_u64 v[230:231], s[26:27], 0, v[134:135]
	s_mov_b32 m0, s40
	s_nop 0
	global_load_lds_dwordx4 v[230:231], off
	s_waitcnt vmcnt(8)
	s_waitcnt lgkmcnt(0)
	s_barrier
	s_setprio 1
	s_waitcnt lgkmcnt(0)
	v_mfma_f32_16x16x32_bf16 v[126:129], v[146:149], v[194:197], v[126:129]
	v_mfma_f32_16x16x32_bf16 v[122:125], v[164:167], v[194:197], v[122:125]
	v_mfma_f32_16x16x32_bf16 v[110:113], v[146:149], v[202:205], v[110:113]
	v_mfma_f32_16x16x32_bf16 v[106:109], v[164:167], v[202:205], v[106:109]
	v_mfma_f32_16x16x32_bf16 v[94:97], v[146:149], v[210:213], v[94:97]
	v_mfma_f32_16x16x32_bf16 v[90:93], v[164:167], v[210:213], v[90:93]
	v_mfma_f32_16x16x32_bf16 v[78:81], v[146:149], v[218:221], v[78:81]
	v_mfma_f32_16x16x32_bf16 v[74:77], v[164:167], v[218:221], v[74:77]
	v_mfma_f32_16x16x32_bf16 v[126:129], v[160:163], v[198:201], v[126:129]
	v_mfma_f32_16x16x32_bf16 v[122:125], v[168:171], v[198:201], v[122:125]
	v_mfma_f32_16x16x32_bf16 v[110:113], v[160:163], v[206:209], v[110:113]
	v_mfma_f32_16x16x32_bf16 v[106:109], v[168:171], v[206:209], v[106:109]
	v_mfma_f32_16x16x32_bf16 v[94:97], v[160:163], v[214:217], v[94:97]
	v_mfma_f32_16x16x32_bf16 v[90:93], v[168:171], v[214:217], v[90:93]
	v_mfma_f32_16x16x32_bf16 v[78:81], v[160:163], v[222:225], v[78:81]
	v_mfma_f32_16x16x32_bf16 v[74:77], v[168:171], v[222:225], v[74:77]
	s_setprio 0
	s_setprio 1
	v_mfma_f32_16x16x32_bf16 v[118:121], v[178:181], v[194:197], v[118:121]
	v_mfma_f32_16x16x32_bf16 v[114:117], v[186:189], v[194:197], v[114:117]
	v_mfma_f32_16x16x32_bf16 v[102:105], v[178:181], v[202:205], v[102:105]
	v_mfma_f32_16x16x32_bf16 v[98:101], v[186:189], v[202:205], v[98:101]
	v_mfma_f32_16x16x32_bf16 v[86:89], v[178:181], v[210:213], v[86:89]
	v_mfma_f32_16x16x32_bf16 v[82:85], v[186:189], v[210:213], v[82:85]
	v_mfma_f32_16x16x32_bf16 v[70:73], v[178:181], v[218:221], v[70:73]
	v_mfma_f32_16x16x32_bf16 v[66:69], v[186:189], v[218:221], v[66:69]
	v_mfma_f32_16x16x32_bf16 v[118:121], v[182:185], v[198:201], v[118:121]
	v_mfma_f32_16x16x32_bf16 v[114:117], v[190:193], v[198:201], v[114:117]
	v_mfma_f32_16x16x32_bf16 v[102:105], v[182:185], v[206:209], v[102:105]
	v_mfma_f32_16x16x32_bf16 v[98:101], v[190:193], v[206:209], v[98:101]
	v_mfma_f32_16x16x32_bf16 v[86:89], v[182:185], v[214:217], v[86:89]
	v_mfma_f32_16x16x32_bf16 v[82:85], v[190:193], v[214:217], v[82:85]
	v_mfma_f32_16x16x32_bf16 v[70:73], v[182:185], v[222:225], v[70:73]
	v_mfma_f32_16x16x32_bf16 v[66:69], v[190:193], v[222:225], v[66:69]
	s_setprio 0
	s_barrier
	s_add_i32 s26, s54, s36
	v_lshl_add_u64 v[150:151], v[150:151], 0, s[10:11]
	s_mov_b32 m0, s26
	ds_read_b128 v[194:197], v157 offset:49152
	ds_read_b128 v[198:201], v157 offset:50176
	ds_read_b128 v[202:205], v157 offset:51200
	ds_read_b128 v[206:209], v157 offset:52224
	ds_read_b128 v[210:213], v157 offset:53248
	ds_read_b128 v[214:217], v157 offset:54272
	ds_read_b128 v[218:221], v157 offset:55296
	ds_read_b128 v[222:225], v157 offset:56320
	global_load_lds_dwordx4 v[150:151], off
	s_add_i32 m0, s26, 0x2000
	s_add_u32 s26, s30, 0x40080
	v_lshl_add_u64 v[150:151], v[172:173], 0, s[10:11]
	s_addc_u32 s27, s31, 0
	s_add_i32 s30, s55, s36
	global_load_lds_dwordx4 v[150:151], off
	v_lshl_add_u64 v[150:151], s[26:27], 0, v[132:133]
	s_mov_b32 m0, s30
	s_nop 0
	global_load_lds_dwordx4 v[150:151], off
	v_lshl_add_u64 v[150:151], s[26:27], 0, v[136:137]
	s_add_i32 m0, s30, 0x2000
	s_nop 0
	global_load_lds_dwordx4 v[150:151], off
	v_lshl_add_u64 v[150:151], v[226:227], 0, s[10:11]
	s_mov_b32 m0, s42
	s_nop 0
	global_load_lds_dwordx4 v[150:151], off
	v_lshl_add_u64 v[150:151], v[228:229], 0, s[10:11]
	s_mov_b32 m0, s43
	s_nop 0
	global_load_lds_dwordx4 v[150:151], off
	s_waitcnt vmcnt(8)
	s_waitcnt lgkmcnt(0)
	s_barrier
	s_setprio 1
	s_waitcnt lgkmcnt(0)
	v_mfma_f32_16x16x32_bf16 v[62:65], v[146:149], v[194:197], v[62:65]
	v_mfma_f32_16x16x32_bf16 v[58:61], v[164:167], v[194:197], v[58:61]
	v_mfma_f32_16x16x32_bf16 v[46:49], v[146:149], v[202:205], v[46:49]
	v_mfma_f32_16x16x32_bf16 v[42:45], v[164:167], v[202:205], v[42:45]
	v_mfma_f32_16x16x32_bf16 v[30:33], v[146:149], v[210:213], v[30:33]
	v_mfma_f32_16x16x32_bf16 v[26:29], v[164:167], v[210:213], v[26:29]
	v_mfma_f32_16x16x32_bf16 v[14:17], v[146:149], v[218:221], v[14:17]
	v_mfma_f32_16x16x32_bf16 v[10:13], v[164:167], v[218:221], v[10:13]
	v_mfma_f32_16x16x32_bf16 v[62:65], v[160:163], v[198:201], v[62:65]
	v_mfma_f32_16x16x32_bf16 v[58:61], v[168:171], v[198:201], v[58:61]
	v_mfma_f32_16x16x32_bf16 v[46:49], v[160:163], v[206:209], v[46:49]
	v_mfma_f32_16x16x32_bf16 v[42:45], v[168:171], v[206:209], v[42:45]
	v_mfma_f32_16x16x32_bf16 v[30:33], v[160:163], v[214:217], v[30:33]
	v_mfma_f32_16x16x32_bf16 v[26:29], v[168:171], v[214:217], v[26:29]
	v_mfma_f32_16x16x32_bf16 v[14:17], v[160:163], v[222:225], v[14:17]
	v_mfma_f32_16x16x32_bf16 v[10:13], v[168:171], v[222:225], v[10:13]
	s_setprio 0
	s_setprio 1
	v_mfma_f32_16x16x32_bf16 v[54:57], v[178:181], v[194:197], v[54:57]
	v_mfma_f32_16x16x32_bf16 v[50:53], v[186:189], v[194:197], v[50:53]
	v_mfma_f32_16x16x32_bf16 v[38:41], v[178:181], v[202:205], v[38:41]
	v_mfma_f32_16x16x32_bf16 v[34:37], v[186:189], v[202:205], v[34:37]
	v_mfma_f32_16x16x32_bf16 v[22:25], v[178:181], v[210:213], v[22:25]
	v_mfma_f32_16x16x32_bf16 v[18:21], v[186:189], v[210:213], v[18:21]
	v_mfma_f32_16x16x32_bf16 v[6:9], v[178:181], v[218:221], v[6:9]
	v_mfma_f32_16x16x32_bf16 v[2:5], v[186:189], v[218:221], v[2:5]
	v_mfma_f32_16x16x32_bf16 v[54:57], v[182:185], v[198:201], v[54:57]
	v_mfma_f32_16x16x32_bf16 v[50:53], v[190:193], v[198:201], v[50:53]
	v_mfma_f32_16x16x32_bf16 v[38:41], v[182:185], v[206:209], v[38:41]
	v_mfma_f32_16x16x32_bf16 v[34:37], v[190:193], v[206:209], v[34:37]
	v_mfma_f32_16x16x32_bf16 v[22:25], v[182:185], v[214:217], v[22:25]
	v_mfma_f32_16x16x32_bf16 v[18:21], v[190:193], v[214:217], v[18:21]
	v_mfma_f32_16x16x32_bf16 v[6:9], v[182:185], v[222:225], v[6:9]
	v_mfma_f32_16x16x32_bf16 v[2:5], v[190:193], v[222:225], v[2:5]
	s_setprio 0
	s_barrier
	s_add_i32 s53, s53, 2
	s_add_u32 s51, s51, 0x100
	s_addc_u32 s52, s52, 0
	s_cmp_gt_u32 s53, 13
	s_mov_b64 s[26:27], s[28:29]
	s_cbranch_scc0 .LBB0_1590
	s_branch .Lpeel_exit_1590
	.p2alignl 6, 3212836864

.LBB0_1683:
	s_add_u32 s49, s28, 0x100
	s_addc_u32 s50, s29, 0
	s_mov_b32 s51, -2
	s_waitcnt lgkmcnt(0)
	ds_read_b128 v[144:147], v151
	ds_read_b128 v[156:159], v151 offset:1024
	ds_read_b128 v[160:163], v151 offset:2048
	ds_read_b128 v[164:167], v151 offset:3072
	ds_read_b128 v[168:171], v152
	ds_read_b128 v[176:179], v152 offset:1024
	ds_read_b128 v[180:183], v152 offset:2048
	ds_read_b128 v[184:187], v152 offset:3072
	s_add_u32 s28, s26, 0x100
	s_addc_u32 s29, s27, 0
	s_cmp_eq_u32 s51, 40
	s_cselect_b32 s35, s7, s29
	s_cselect_b32 s34, s6, s28
	s_cselect_b32 s31, s25, s50
	s_cselect_b32 s30, s24, s49
	v_lshl_add_u64 v[172:173], s[26:27], 0, v[136:137]
	s_add_i32 m0, s16, 0xc000
	ds_read_b128 v[188:191], v153
	ds_read_b128 v[192:195], v153 offset:1024
	ds_read_b128 v[196:199], v153 offset:2048
	ds_read_b128 v[200:203], v153 offset:3072
	ds_read_b128 v[204:207], v153 offset:4096
	ds_read_b128 v[208:211], v153 offset:5120
	ds_read_b128 v[212:215], v153 offset:6144
	ds_read_b128 v[216:219], v153 offset:7168
	global_load_lds_dwordx4 v[172:173], off
	v_lshl_add_u64 v[172:173], s[26:27], 0, v[138:139]
	s_add_i32 m0, s16, 0xe000
	s_nop 0
	global_load_lds_dwordx4 v[172:173], off
	s_waitcnt vmcnt(8)
	s_waitcnt lgkmcnt(0)
	s_barrier
	s_setprio 1
	s_waitcnt lgkmcnt(0)
	v_mfma_f32_16x16x32_bf16 v[124:127], v[144:147], v[188:191], 0
	v_mfma_f32_16x16x32_bf16 v[120:123], v[160:163], v[188:191], 0
	v_mfma_f32_16x16x32_bf16 v[108:111], v[144:147], v[196:199], 0
	v_mfma_f32_16x16x32_bf16 v[104:107], v[160:163], v[196:199], 0
	v_mfma_f32_16x16x32_bf16 v[92:95], v[144:147], v[204:207], 0
	v_mfma_f32_16x16x32_bf16 v[88:91], v[160:163], v[204:207], 0
	v_mfma_f32_16x16x32_bf16 v[76:79], v[144:147], v[212:215], 0
	v_mfma_f32_16x16x32_bf16 v[72:75], v[160:163], v[212:215], 0
	v_mfma_f32_16x16x32_bf16 v[124:127], v[156:159], v[192:195], v[124:127]
	v_mfma_f32_16x16x32_bf16 v[120:123], v[164:167], v[192:195], v[120:123]
	v_mfma_f32_16x16x32_bf16 v[108:111], v[156:159], v[200:203], v[108:111]
	v_mfma_f32_16x16x32_bf16 v[104:107], v[164:167], v[200:203], v[104:107]
	v_mfma_f32_16x16x32_bf16 v[92:95], v[156:159], v[208:211], v[92:95]
	v_mfma_f32_16x16x32_bf16 v[88:91], v[164:167], v[208:211], v[88:91]
	v_mfma_f32_16x16x32_bf16 v[76:79], v[156:159], v[216:219], v[76:79]
	v_mfma_f32_16x16x32_bf16 v[72:75], v[164:167], v[216:219], v[72:75]
	s_setprio 0
	s_setprio 1
	v_mfma_f32_16x16x32_bf16 v[116:119], v[168:171], v[188:191], 0
	v_mfma_f32_16x16x32_bf16 v[112:115], v[180:183], v[188:191], 0
	v_mfma_f32_16x16x32_bf16 v[100:103], v[168:171], v[196:199], 0
	v_mfma_f32_16x16x32_bf16 v[96:99], v[180:183], v[196:199], 0
	v_mfma_f32_16x16x32_bf16 v[84:87], v[168:171], v[204:207], 0
	v_mfma_f32_16x16x32_bf16 v[80:83], v[180:183], v[204:207], 0
	v_mfma_f32_16x16x32_bf16 v[68:71], v[168:171], v[212:215], 0
	v_mfma_f32_16x16x32_bf16 v[64:67], v[180:183], v[212:215], 0
	v_mfma_f32_16x16x32_bf16 v[116:119], v[176:179], v[192:195], v[116:119]
	v_mfma_f32_16x16x32_bf16 v[112:115], v[184:187], v[192:195], v[112:115]
	v_mfma_f32_16x16x32_bf16 v[100:103], v[176:179], v[200:203], v[100:103]
	v_mfma_f32_16x16x32_bf16 v[96:99], v[184:187], v[200:203], v[96:99]
	v_mfma_f32_16x16x32_bf16 v[84:87], v[176:179], v[208:211], v[84:87]
	v_mfma_f32_16x16x32_bf16 v[80:83], v[184:187], v[208:211], v[80:83]
	v_mfma_f32_16x16x32_bf16 v[68:71], v[176:179], v[216:219], v[68:71]
	v_mfma_f32_16x16x32_bf16 v[64:67], v[184:187], v[216:219], v[64:67]
	s_setprio 0
	s_barrier
	s_add_i32 s26, s43, s15
	v_lshl_add_u64 v[172:173], s[30:31], 0, v[130:131]
	s_mov_b32 m0, s26
	ds_read_b128 v[188:191], v153 offset:16384
	ds_read_b128 v[192:195], v153 offset:17408
	ds_read_b128 v[196:199], v153 offset:18432
	ds_read_b128 v[200:203], v153 offset:19456
	ds_read_b128 v[204:207], v153 offset:20480
	ds_read_b128 v[208:211], v153 offset:21504
	ds_read_b128 v[212:215], v153 offset:22528
	ds_read_b128 v[216:219], v153 offset:23552
	global_load_lds_dwordx4 v[172:173], off
	s_add_i32 m0, s26, 0x2000
	s_add_u32 s26, s30, 0xb0000
	v_lshl_add_u64 v[220:221], s[30:31], 0, v[134:135]
	s_addc_u32 s27, s31, 0
	s_add_i32 s52, s44, s15
	global_load_lds_dwordx4 v[220:221], off
	v_lshl_add_u64 v[222:223], s[26:27], 0, v[130:131]
	s_mov_b32 m0, s52
	v_lshl_add_u64 v[224:225], s[34:35], 0, v[132:133]
	global_load_lds_dwordx4 v[222:223], off
	v_lshl_add_u64 v[222:223], s[26:27], 0, v[134:135]
	s_add_i32 m0, s52, 0x2000
	s_nop 0
	global_load_lds_dwordx4 v[222:223], off
	v_lshl_add_u64 v[222:223], s[34:35], 0, v[128:129]
	s_mov_b32 m0, s16
	s_nop 0
	global_load_lds_dwordx4 v[222:223], off
	s_mov_b32 m0, s17
	s_nop 0
	global_load_lds_dwordx4 v[224:225], off
	s_waitcnt vmcnt(8)
	s_waitcnt lgkmcnt(0)
	s_barrier
	s_setprio 1
	s_waitcnt lgkmcnt(0)
	v_mfma_f32_16x16x32_bf16 v[60:63], v[144:147], v[188:191], 0
	v_mfma_f32_16x16x32_bf16 v[56:59], v[160:163], v[188:191], 0
	v_mfma_f32_16x16x32_bf16 v[44:47], v[144:147], v[196:199], 0
	v_mfma_f32_16x16x32_bf16 v[40:43], v[160:163], v[196:199], 0
	v_mfma_f32_16x16x32_bf16 v[28:31], v[144:147], v[204:207], 0
	v_mfma_f32_16x16x32_bf16 v[24:27], v[160:163], v[204:207], 0
	v_mfma_f32_16x16x32_bf16 v[12:15], v[144:147], v[212:215], 0
	v_mfma_f32_16x16x32_bf16 v[8:11], v[160:163], v[212:215], 0
	v_mfma_f32_16x16x32_bf16 v[60:63], v[156:159], v[192:195], v[60:63]
	v_mfma_f32_16x16x32_bf16 v[56:59], v[164:167], v[192:195], v[56:59]
	v_mfma_f32_16x16x32_bf16 v[44:47], v[156:159], v[200:203], v[44:47]
	v_mfma_f32_16x16x32_bf16 v[40:43], v[164:167], v[200:203], v[40:43]
	v_mfma_f32_16x16x32_bf16 v[28:31], v[156:159], v[208:211], v[28:31]
	v_mfma_f32_16x16x32_bf16 v[24:27], v[164:167], v[208:211], v[24:27]
	v_mfma_f32_16x16x32_bf16 v[12:15], v[156:159], v[216:219], v[12:15]
	v_mfma_f32_16x16x32_bf16 v[8:11], v[164:167], v[216:219], v[8:11]
	s_setprio 0
	s_setprio 1
	v_mfma_f32_16x16x32_bf16 v[52:55], v[168:171], v[188:191], 0
	v_mfma_f32_16x16x32_bf16 v[48:51], v[180:183], v[188:191], 0
	v_mfma_f32_16x16x32_bf16 v[36:39], v[168:171], v[196:199], 0
	v_mfma_f32_16x16x32_bf16 v[32:35], v[180:183], v[196:199], 0
	v_mfma_f32_16x16x32_bf16 v[20:23], v[168:171], v[204:207], 0
	v_mfma_f32_16x16x32_bf16 v[16:19], v[180:183], v[204:207], 0
	v_mfma_f32_16x16x32_bf16 v[4:7], v[168:171], v[212:215], 0
	v_mfma_f32_16x16x32_bf16 v[0:3], v[180:183], v[212:215], 0
	v_mfma_f32_16x16x32_bf16 v[52:55], v[176:179], v[192:195], v[52:55]
	v_mfma_f32_16x16x32_bf16 v[48:51], v[184:187], v[192:195], v[48:51]
	v_mfma_f32_16x16x32_bf16 v[36:39], v[176:179], v[200:203], v[36:39]
	v_mfma_f32_16x16x32_bf16 v[32:35], v[184:187], v[200:203], v[32:35]
	v_mfma_f32_16x16x32_bf16 v[20:23], v[176:179], v[208:211], v[20:23]
	v_mfma_f32_16x16x32_bf16 v[16:19], v[184:187], v[208:211], v[16:19]
	v_mfma_f32_16x16x32_bf16 v[4:7], v[176:179], v[216:219], v[4:7]
	v_mfma_f32_16x16x32_bf16 v[0:3], v[184:187], v[216:219], v[0:3]
	s_setprio 0
	s_barrier
	s_add_i32 s52, 0, 0x18000
	v_add_u32_e32 v155, s52, v149
	s_add_i32 s53, 0, 0x1c000
	ds_read_b128 v[144:147], v155
	ds_read_b128 v[156:159], v155 offset:1024
	ds_read_b128 v[160:163], v155 offset:2048
	ds_read_b128 v[164:167], v155 offset:3072
	v_add_u32_e32 v155, s53, v149
	ds_read_b128 v[168:171], v155
	ds_read_b128 v[176:179], v155 offset:1024
	ds_read_b128 v[180:183], v155 offset:2048
	ds_read_b128 v[184:187], v155 offset:3072
	s_add_u32 s26, s34, 0xb0000
	s_addc_u32 s27, s35, 0
	s_mov_b32 m0, s36
	v_lshl_add_u64 v[226:227], s[26:27], 0, v[128:129]
	ds_read_b128 v[188:191], v153 offset:32768
	ds_read_b128 v[192:195], v153 offset:33792
	ds_read_b128 v[196:199], v153 offset:34816
	ds_read_b128 v[200:203], v153 offset:35840
	ds_read_b128 v[204:207], v153 offset:36864
	ds_read_b128 v[208:211], v153 offset:37888
	ds_read_b128 v[212:215], v153 offset:38912
	ds_read_b128 v[216:219], v153 offset:39936
	global_load_lds_dwordx4 v[226:227], off
	v_lshl_add_u64 v[226:227], s[26:27], 0, v[132:133]
	s_mov_b32 m0, s37
	s_nop 0
	global_load_lds_dwordx4 v[226:227], off
	s_waitcnt vmcnt(8)
	s_waitcnt lgkmcnt(0)
	s_barrier
	s_setprio 1
	s_waitcnt lgkmcnt(0)
	v_mfma_f32_16x16x32_bf16 v[124:127], v[144:147], v[188:191], v[124:127]
	v_mfma_f32_16x16x32_bf16 v[120:123], v[160:163], v[188:191], v[120:123]
	v_mfma_f32_16x16x32_bf16 v[108:111], v[144:147], v[196:199], v[108:111]
	v_mfma_f32_16x16x32_bf16 v[104:107], v[160:163], v[196:199], v[104:107]
	v_mfma_f32_16x16x32_bf16 v[92:95], v[144:147], v[204:207], v[92:95]
	v_mfma_f32_16x16x32_bf16 v[88:91], v[160:163], v[204:207], v[88:91]
	v_mfma_f32_16x16x32_bf16 v[76:79], v[144:147], v[212:215], v[76:79]
	v_mfma_f32_16x16x32_bf16 v[72:75], v[160:163], v[212:215], v[72:75]
	v_mfma_f32_16x16x32_bf16 v[124:127], v[156:159], v[192:195], v[124:127]
	v_mfma_f32_16x16x32_bf16 v[120:123], v[164:167], v[192:195], v[120:123]
	v_mfma_f32_16x16x32_bf16 v[108:111], v[156:159], v[200:203], v[108:111]
	v_mfma_f32_16x16x32_bf16 v[104:107], v[164:167], v[200:203], v[104:107]
	v_mfma_f32_16x16x32_bf16 v[92:95], v[156:159], v[208:211], v[92:95]
	v_mfma_f32_16x16x32_bf16 v[88:91], v[164:167], v[208:211], v[88:91]
	v_mfma_f32_16x16x32_bf16 v[76:79], v[156:159], v[216:219], v[76:79]
	v_mfma_f32_16x16x32_bf16 v[72:75], v[164:167], v[216:219], v[72:75]
	s_setprio 0
	s_setprio 1
	v_mfma_f32_16x16x32_bf16 v[116:119], v[168:171], v[188:191], v[116:119]
	v_mfma_f32_16x16x32_bf16 v[112:115], v[180:183], v[188:191], v[112:115]
	v_mfma_f32_16x16x32_bf16 v[100:103], v[168:171], v[196:199], v[100:103]
	v_mfma_f32_16x16x32_bf16 v[96:99], v[180:183], v[196:199], v[96:99]
	v_mfma_f32_16x16x32_bf16 v[84:87], v[168:171], v[204:207], v[84:87]
	v_mfma_f32_16x16x32_bf16 v[80:83], v[180:183], v[204:207], v[80:83]
	v_mfma_f32_16x16x32_bf16 v[68:71], v[168:171], v[212:215], v[68:71]
	v_mfma_f32_16x16x32_bf16 v[64:67], v[180:183], v[212:215], v[64:67]
	v_mfma_f32_16x16x32_bf16 v[116:119], v[176:179], v[192:195], v[116:119]
	v_mfma_f32_16x16x32_bf16 v[112:115], v[184:187], v[192:195], v[112:115]
	v_mfma_f32_16x16x32_bf16 v[100:103], v[176:179], v[200:203], v[100:103]
	v_mfma_f32_16x16x32_bf16 v[96:99], v[184:187], v[200:203], v[96:99]
	v_mfma_f32_16x16x32_bf16 v[84:87], v[176:179], v[208:211], v[84:87]
	v_mfma_f32_16x16x32_bf16 v[80:83], v[184:187], v[208:211], v[80:83]
	v_mfma_f32_16x16x32_bf16 v[68:71], v[176:179], v[216:219], v[68:71]
	v_mfma_f32_16x16x32_bf16 v[64:67], v[184:187], v[216:219], v[64:67]
	s_setprio 0
	s_barrier
	s_add_i32 s26, s52, s15
	v_lshl_add_u64 v[172:173], v[172:173], 0, s[20:21]
	s_mov_b32 m0, s26
	ds_read_b128 v[188:191], v153 offset:49152
	ds_read_b128 v[192:195], v153 offset:50176
	ds_read_b128 v[196:199], v153 offset:51200
	ds_read_b128 v[200:203], v153 offset:52224
	ds_read_b128 v[204:207], v153 offset:53248
	ds_read_b128 v[208:211], v153 offset:54272
	ds_read_b128 v[212:215], v153 offset:55296
	ds_read_b128 v[216:219], v153 offset:56320
	global_load_lds_dwordx4 v[172:173], off
	s_add_i32 m0, s26, 0x2000
	s_add_u32 s26, s30, 0xb0080
	v_lshl_add_u64 v[172:173], v[220:221], 0, s[20:21]
	s_addc_u32 s27, s31, 0
	s_add_i32 s30, s53, s15
	global_load_lds_dwordx4 v[172:173], off
	v_lshl_add_u64 v[172:173], s[26:27], 0, v[130:131]
	s_mov_b32 m0, s30
	s_nop 0
	global_load_lds_dwordx4 v[172:173], off
	v_lshl_add_u64 v[172:173], s[26:27], 0, v[134:135]
	s_add_i32 m0, s30, 0x2000
	s_nop 0
	global_load_lds_dwordx4 v[172:173], off
	v_lshl_add_u64 v[172:173], v[222:223], 0, s[20:21]
	s_mov_b32 m0, s39
	s_nop 0
	global_load_lds_dwordx4 v[172:173], off
	v_lshl_add_u64 v[172:173], v[224:225], 0, s[20:21]
	s_mov_b32 m0, s40
	s_nop 0
	global_load_lds_dwordx4 v[172:173], off
	s_waitcnt vmcnt(8)
	s_waitcnt lgkmcnt(0)
	s_barrier
	s_setprio 1
	s_waitcnt lgkmcnt(0)
	v_mfma_f32_16x16x32_bf16 v[60:63], v[144:147], v[188:191], v[60:63]
	v_mfma_f32_16x16x32_bf16 v[56:59], v[160:163], v[188:191], v[56:59]
	v_mfma_f32_16x16x32_bf16 v[44:47], v[144:147], v[196:199], v[44:47]
	v_mfma_f32_16x16x32_bf16 v[40:43], v[160:163], v[196:199], v[40:43]
	v_mfma_f32_16x16x32_bf16 v[28:31], v[144:147], v[204:207], v[28:31]
	v_mfma_f32_16x16x32_bf16 v[24:27], v[160:163], v[204:207], v[24:27]
	v_mfma_f32_16x16x32_bf16 v[12:15], v[144:147], v[212:215], v[12:15]
	v_mfma_f32_16x16x32_bf16 v[8:11], v[160:163], v[212:215], v[8:11]
	v_mfma_f32_16x16x32_bf16 v[60:63], v[156:159], v[192:195], v[60:63]
	v_mfma_f32_16x16x32_bf16 v[56:59], v[164:167], v[192:195], v[56:59]
	v_mfma_f32_16x16x32_bf16 v[44:47], v[156:159], v[200:203], v[44:47]
	v_mfma_f32_16x16x32_bf16 v[40:43], v[164:167], v[200:203], v[40:43]
	v_mfma_f32_16x16x32_bf16 v[28:31], v[156:159], v[208:211], v[28:31]
	v_mfma_f32_16x16x32_bf16 v[24:27], v[164:167], v[208:211], v[24:27]
	v_mfma_f32_16x16x32_bf16 v[12:15], v[156:159], v[216:219], v[12:15]
	v_mfma_f32_16x16x32_bf16 v[8:11], v[164:167], v[216:219], v[8:11]
	s_setprio 0
	s_setprio 1
	v_mfma_f32_16x16x32_bf16 v[52:55], v[168:171], v[188:191], v[52:55]
	v_mfma_f32_16x16x32_bf16 v[48:51], v[180:183], v[188:191], v[48:51]
	v_mfma_f32_16x16x32_bf16 v[36:39], v[168:171], v[196:199], v[36:39]
	v_mfma_f32_16x16x32_bf16 v[32:35], v[180:183], v[196:199], v[32:35]
	v_mfma_f32_16x16x32_bf16 v[20:23], v[168:171], v[204:207], v[20:23]
	v_mfma_f32_16x16x32_bf16 v[16:19], v[180:183], v[204:207], v[16:19]
	v_mfma_f32_16x16x32_bf16 v[4:7], v[168:171], v[212:215], v[4:7]
	v_mfma_f32_16x16x32_bf16 v[0:3], v[180:183], v[212:215], v[0:3]
	v_mfma_f32_16x16x32_bf16 v[52:55], v[176:179], v[192:195], v[52:55]
	v_mfma_f32_16x16x32_bf16 v[48:51], v[184:187], v[192:195], v[48:51]
	v_mfma_f32_16x16x32_bf16 v[36:39], v[176:179], v[200:203], v[36:39]
	v_mfma_f32_16x16x32_bf16 v[32:35], v[184:187], v[200:203], v[32:35]
	v_mfma_f32_16x16x32_bf16 v[20:23], v[176:179], v[208:211], v[20:23]
	v_mfma_f32_16x16x32_bf16 v[16:19], v[184:187], v[208:211], v[16:19]
	v_mfma_f32_16x16x32_bf16 v[4:7], v[176:179], v[216:219], v[4:7]
	v_mfma_f32_16x16x32_bf16 v[0:3], v[184:187], v[216:219], v[0:3]
	s_setprio 0
	s_barrier
	s_add_i32 s51, s51, 2
	s_add_u32 s49, s49, 0x100
	s_addc_u32 s50, s50, 0
	s_cmp_gt_u32 s51, 41
	s_mov_b64 s[26:27], s[28:29]
	s_cbranch_scc0 .LBB0_1684
	s_branch .Lpeel_exit_1684
	.p2alignl 6, 3212836864
